# RWKV chain waves after barrier X: LDS reads hoisted ahead of consumers with renamed destinations and counted lgkmcnt waits (tool-driven), on top of BCE
# baseline (speedup 1.0000x reference)
.LBB0_362:
	s_or_b64 exec, exec, s[28:29]
	s_waitcnt lgkmcnt(0)
	s_barrier
	ds_read_b128 v[40:43], v214 offset:9216
	ds_read_b128 v[48:51], v214 offset:18496
	ds_read_b128 v[56:59], v214 offset:9280
	ds_read_b128 v[60:63], v214 offset:23040
	ds_read_b128 v[36:39], v214 offset:18432
	s_nop 0
	s_nop 0
	s_nop 0
	ds_read_b128 v[64:67], v214 offset:13824
	s_waitcnt lgkmcnt(1)
	v_mfma_f32_16x16x32_f16 v[52:55], v[40:43], v[36:39], 0
	s_nop 0
	s_nop 0
	s_nop 0
	ds_read_b128 v[68:71], v214 offset:13888
	ds_read_b128 v[72:75], v214 offset:23104
	v_add_u32_e32 v80, 0x1000, v220
	s_nop 0
	v_mfma_f32_16x16x32_f16 v[52:55], v[56:59], v[48:51], v[52:55]
	v_mov_b32_e32 v82, v3
	v_mov_b32_e32 v83, v3
	v_mov_b32_e32 v86, v3
	v_mfma_f32_16x16x32_f16 v[44:47], v[36:39], v[40:43], 0
	s_nop 3
	v_cvt_f16_f32_e32 v0, v52
	v_cvt_f16_f32_e32 v1, v54
	v_cvt_f16_f32_e32 v2, v55
	v_mfma_f32_16x16x32_f16 v[44:47], v[48:51], v[56:59], v[44:47]
	v_cndmask_b32_e64 v79, 0, v0, s[12:13]
	v_cvt_f16_f32_e32 v0, v53
	v_cndmask_b32_e64 v54, 0, v1, s[18:19]
	s_nop 0
	v_mfma_f32_16x16x32_f16 v[40:43], v[60:63], v[40:43], 0
	v_cndmask_b32_e64 v55, 0, v2, s[22:23]
	s_nop 1
	v_cndmask_b32_e64 v76, 0, v44, s[10:11]
	v_cndmask_b32_e64 v77, 0, v45, s[14:15]
	s_nop 0
	s_waitcnt lgkmcnt(2)
	v_mfma_f32_16x16x32_f16 v[36:39], v[36:39], v[64:67], 0
	v_cndmask_b32_e64 v52, 0, v46, s[16:17]
	v_cndmask_b32_e64 v78, 0, v47, s[20:21]
	v_cndmask_b32_e64 v53, v0, 0, s[10:11]
	v_mfma_f32_16x16x32_f16 v[44:47], v[60:63], v[64:67], 0
	v_cvt_pk_f16_f32 v1, v52, v78
	v_cvt_pk_f16_f32 v0, v76, v77
	v_mov_b32_e32 v2, v3
	s_nop 0
	s_waitcnt lgkmcnt(0)
	v_mfma_f32_16x16x32_f16 v[60:63], v[72:75], v[56:59], v[40:43]
	v_add_f32_e32 v56, v215, v76
	v_add_f32_e32 v57, v217, v77
	v_add_f32_e32 v58, v218, v52
	v_mfma_f32_16x16x32_f16 v[40:43], v[48:51], v[68:71], v[36:39]
	v_add_f32_e32 v59, v219, v78
	v_cvt_pk_f16_f32 v67, v26, v27
	v_cvt_pk_f16_f32 v66, v24, v25
	v_pack_b32_f16 v37, v54, v55
	v_pack_b32_f16 v36, v79, v53
	v_mov_b32_e32 v38, v3
	v_mov_b32_e32 v39, v3
	v_mfma_f32_16x16x32_f16 v[52:55], v[72:75], v[68:71], v[44:47]
	ds_read2_b64 v[68:71], v220 offset0:8 offset1:12
	v_cvt_pk_f16_f32 v65, v30, v31
	v_cvt_pk_f16_f32 v64, v28, v29
	v_mfma_f32_16x16x32_f16 v[48:51], v[0:3], v[36:39], 0
	v_cvt_pk_f16_f32 v45, v58, v59
	v_cvt_pk_f16_f32 v44, v56, v57
	v_mov_b32_e32 v46, v3
	v_mfma_f32_16x16x32_f16 v[36:39], v[36:39], v[0:3], 0
	v_mov_b32_e32 v47, v3
	s_nop 2
	v_cvt_pk_f16_f32 v1, v50, v51
	v_cvt_pk_f16_f32 v0, v48, v49
	v_mov_b32_e32 v50, v3
	v_mov_b32_e32 v51, v3
	v_cvt_pk_f16_f32 v49, v38, v39
	v_cvt_pk_f16_f32 v48, v36, v37
	v_mfma_f32_16x16x32_f16 v[44:47], v[0:3], v[44:47], v[56:59]
	v_mov_b32_e32 v87, v3
	v_mov_b32_e32 v90, v3
	v_mov_b32_e32 v91, v3
	v_mfma_f32_16x16x32_f16 v[36:39], v[48:51], v[0:3], 0
	ds_read2_b64 v[128:131], v220 offset1:4
	v_cvt_pk_f16_f32 v59, v34, v35
	v_cvt_pk_f16_f32 v58, v32, v33
	v_cvt_pk_f16_f32 v57, v22, v23
	v_mfma_f32_16x16x32_f16 v[48:51], v[0:3], v[48:51], 0
	v_cvt_pk_f16_f32 v56, v20, v21
	s_nop 2
	v_cvt_pk_f16_f32 v1, v38, v39
	v_cvt_pk_f16_f32 v0, v36, v37
	v_cvt_pk_f16_f32 v37, v46, v47
	v_cvt_pk_f16_f32 v36, v44, v45
	v_mov_b32_e32 v38, v3
	v_mov_b32_e32 v39, v3
	v_cvt_f16_f32_e32 v52, v52
	s_add_i32 s27, s26, 1
	v_mfma_f32_16x16x32_f16 v[44:47], v[0:3], v[36:39], v[44:47]
	v_cvt_pk_f16_f32 v37, v50, v51
	v_cvt_pk_f16_f32 v36, v48, v49
	v_mov_b32_e32 v50, v3
	v_mov_b32_e32 v51, v3
	v_mfma_f32_16x16x32_f16 v[36:39], v[36:39], v[0:3], 0
	s_nop 2
	v_cvt_pk_f16_f32 v1, v46, v47
	v_cvt_pk_f16_f32 v0, v44, v45
	s_nop 2
	v_cvt_pk_f16_f32 v49, v38, v39
	v_cvt_pk_f16_f32 v48, v36, v37
	s_nop 0
	s_nop 0
	s_waitcnt lgkmcnt(0)
	v_mfma_f32_16x16x32_f16 v[36:39], v[128:131], v[56:59], 0
	v_mfma_f32_16x16x32_f16 v[44:47], v[48:51], v[0:3], v[44:47]
	v_cvt_f16_f32_e32 v0, v60
	v_cvt_f16_f32_e32 v1, v61
	v_cvt_f16_f32_e32 v2, v62
	v_cvt_f16_f32_e32 v48, v63
	v_mfma_f32_16x16x32_f16 v[76:79], v[68:71], v[64:67], v[36:39]
	ds_read2_b64 v[72:75], v80 offset0:64 offset1:68
	ds_read2st64_b64 v[132:135], v221 offset0:20 offset1:25
	ds_read2_b64 v[68:71], v80 offset0:72 offset1:76
	s_nop 0
	s_nop 0
	v_cndmask_b32_e64 v0, 0, v0, s[10:11]
	v_cndmask_b32_e64 v49, 0, v1, s[14:15]
	v_cndmask_b32_e64 v1, 0, v2, s[16:17]
	v_cndmask_b32_e64 v2, 0, v48, s[20:21]
	v_pack_b32_f16 v1, v1, v2
	v_pack_b32_f16 v0, v0, v49
	v_mov_b32_e32 v2, v3
	s_nop 0
	s_waitcnt lgkmcnt(1)
	v_mov_b32_e32 v60, v132
	v_mov_b32_e32 v61, v133
	ds_read2_b64 v[128:131], v236 offset1:80
	v_mov_b32_e32 v62, v3
	v_mov_b32_e32 v63, v3
	v_cvt_f16_f32_e32 v36, v40
	ds_read_b128 v[136:139], v180
	v_cvt_f16_f32_e32 v40, v42
	v_mfma_f32_16x16x32_f16 v[48:51], v[0:3], v[60:63], v[76:79]
	v_cvt_pk_f16_f32 v1, v46, v47
	v_cvt_pk_f16_f32 v0, v44, v45
	v_cvt_f16_f32_e32 v37, v41
	v_mov_b32_e32 v78, v3
	v_mov_b32_e32 v79, v3
	s_nop 2
	v_cvt_pk_f16_f32 v77, v50, v51
	v_cvt_pk_f16_f32 v76, v48, v49
	v_cndmask_b32_e64 v88, v40, 0, s[18:19]
	v_mfma_f32_16x16x32_f16 v[56:59], v[72:75], v[56:59], 0
	v_cndmask_b32_e64 v36, v36, 0, s[12:13]
	v_cndmask_b32_e64 v37, 0, v37, s[10:11]
	v_mov_b32_e32 v74, v3
	v_mfma_f32_16x16x32_f16 v[44:47], v[0:3], v[76:79], 0
	ds_read_b64 v[76:77], v222 offset:5120
	ds_read_b128 v[140:143], v180 offset:64
	v_mov_b32_e32 v75, v3
	s_waitcnt lgkmcnt(4)
	v_mfma_f32_16x16x32_f16 v[56:59], v[68:71], v[64:67], v[56:59]
	s_nop 5
	v_cvt_pk_f16_f32 v1, v46, v47
	v_cvt_pk_f16_f32 v0, v44, v45
	s_nop 0
	s_nop 0
	s_nop 0
	s_nop 0
	s_waitcnt lgkmcnt(3)
	v_mov_b32_e32 v80, v128
	v_mov_b32_e32 v81, v129
	ds_read_b64 v[44:45], v223 offset:5120
	ds_read2_b64 v[144:147], v236 offset0:160 offset1:240
	s_nop 0
	s_waitcnt lgkmcnt(4)
	v_pk_mul_f32 v[50:51], v[22:23], v[138:139]
	v_pk_mul_f32 v[48:49], v[20:21], v[136:137]
	ds_read_b128 v[136:139], v180 offset:128
	s_nop 1
	v_mfma_f32_16x16x32_f16 v[48:51], v[80:83], v[0:3], v[48:51]
	v_cvt_f16_f32_e32 v80, v43
	v_cndmask_b32_e64 v89, v80, 0, s[22:23]
	s_nop 0
	s_waitcnt lgkmcnt(4)
	v_mfma_f32_16x16x32_f16 v[40:43], v[76:79], v[60:63], v[48:51]
	s_nop 3
	s_nop 0
	s_nop 0
	ds_read_b64 v[80:81], v224 offset:5120
	v_mov_b32_e32 v76, v130
	v_mov_b32_e32 v77, v131
	v_mov_b32_e32 v46, v3
	s_nop 0
	s_waitcnt lgkmcnt(4)
	v_pk_mul_f32 v[50:51], v[34:35], v[142:143]
	v_pk_mul_f32 v[48:49], v[32:33], v[140:141]
	v_mov_b32_e32 v47, v3
	ds_read_b128 v[128:131], v180 offset:192
	s_nop 0
	v_mfma_f32_16x16x32_f16 v[48:51], v[76:79], v[0:3], v[48:51]
	s_nop 0
	s_nop 0
	s_waitcnt lgkmcnt(3)
	v_mov_b32_e32 v84, v144
	v_mfma_f32_16x16x32_f16 v[48:51], v[44:47], v[60:63], v[48:51]
	s_nop 0
	s_nop 0
	v_mov_b32_e32 v85, v145
	v_pack_b32_f16 v77, v88, v89
	v_mov_b32_e32 v88, v146
	s_nop 0
	s_waitcnt lgkmcnt(2)
	v_pk_mul_f32 v[46:47], v[30:31], v[138:139]
	v_pk_mul_f32 v[44:45], v[28:29], v[136:137]
	v_mov_b32_e32 v89, v147
	v_pack_b32_f16 v76, v36, v37
	v_mfma_f32_16x16x32_f16 v[44:47], v[84:87], v[0:3], v[44:47]
	ds_read_b64 v[84:85], v225 offset:5120
	v_cndmask_b32_e64 v36, v52, 0, s[12:13]
	v_cvt_f16_f32_e32 v37, v53
	v_cndmask_b32_e64 v37, 0, v37, s[10:11]
	s_nop 0
	s_waitcnt lgkmcnt(2)
	v_mfma_f32_16x16x32_f16 v[44:47], v[80:83], v[60:63], v[44:47]
	s_nop 0
	s_nop 0
	v_pack_b32_f16 v72, v36, v37
	ds_read_b128 v[68:71], v226 offset:9216
	ds_read_b128 v[94:97], v226 offset:9280
	s_nop 0
	s_waitcnt lgkmcnt(3)
	v_pk_mul_f32 v[82:83], v[26:27], v[130:131]
	ds_read_b128 v[64:67], v226 offset:18432
	v_pk_mul_f32 v[80:81], v[24:25], v[128:129]
	s_nop 0
	ds_read_b128 v[98:101], v226 offset:23104
	v_mfma_f32_16x16x32_f16 v[78:81], v[88:91], v[0:3], v[80:83]
	ds_read_b128 v[90:93], v226 offset:18496
	s_nop 1
	v_cvt_f16_f32_e32 v82, v54
	v_cvt_f16_f32_e32 v83, v55
	s_nop 0
	s_waitcnt lgkmcnt(5)
	v_mfma_f32_16x16x32_f16 v[52:55], v[84:87], v[60:63], v[78:81]
	ds_read_b128 v[86:89], v226 offset:13824
	s_nop 1
	v_cndmask_b32_e64 v78, v82, 0, s[18:19]
	v_cndmask_b32_e64 v79, v83, 0, s[22:23]
	v_pack_b32_f16 v73, v78, v79
	v_mov_b32_e32 v78, v3
	v_mov_b32_e32 v79, v3
	v_add_u32_e32 v80, s77, v122
	v_add_u32_e32 v81, s76, v235
	v_mfma_f32_16x16x32_f16 v[56:59], v[76:79], v[0:3], v[56:59]
	ds_read_b128 v[76:79], v226 offset:23040
	v_subrev_u32_e32 v102, 64, v80
	v_add_u32_e32 v0, 0xff, v81
	v_mfma_f32_16x16x32_f16 v[58:61], v[72:75], v[60:63], v[56:59]
	v_cndmask_b32_e64 v0, v0, v102, s[2:3]
	v_add_u32_e32 v0, v0, v173
	v_mad_i64_i32 v[0:1], s[28:29], v0, s91, v[126:127]
	s_nop 0
	s_waitcnt lgkmcnt(4)
	v_mfma_f32_16x16x32_f16 v[82:85], v[68:71], v[64:67], 0
	s_nop 2
	v_cvt_f16_f32_e32 v2, v58
	v_cvt_f16_f32_e32 v60, v60
	ds_read_b128 v[128:131], v226 offset:13888
	global_store_short v[0:1], v2, off
	v_subrev_u32_e32 v0, 63, v80
	v_xad_u32 v1, v102, -2, v166
	v_cvt_f16_f32_e32 v2, v59
	s_nop 0
	v_mfma_f32_16x16x32_f16 v[72:75], v[64:67], v[68:71], 0
	v_cndmask_b32_e64 v0, v1, v0, s[2:3]
	v_add_u32_e32 v0, v0, v173
	v_mad_i64_i32 v[0:1], s[28:29], v0, s91, v[126:127]
	s_nop 0
	s_waitcnt lgkmcnt(2)
	v_mfma_f32_16x16x32_f16 v[62:65], v[64:67], v[86:89], 0
	global_store_short v[0:1], v2, off
	v_subrev_u32_e32 v0, 62, v80
	v_xad_u32 v1, v102, -3, v166
	v_mfma_f32_16x16x32_f16 v[82:85], v[94:97], v[90:93], v[82:85]
	v_cndmask_b32_e64 v36, v1, v0, s[2:3]
	v_add_u32_e32 v36, v36, v173
	s_nop 0
	s_waitcnt lgkmcnt(1)
	v_mfma_f32_16x16x32_f16 v[68:71], v[76:79], v[68:71], 0
	v_mfma_f32_16x16x32_f16 v[86:89], v[76:79], v[86:89], 0
	s_nop 2
	v_cvt_f16_f32_e32 v1, v82
	v_cvt_f16_f32_e32 v2, v83
	v_cvt_f16_f32_e32 v66, v85
	v_mfma_f32_16x16x32_f16 v[72:75], v[90:93], v[94:97], v[72:75]
	v_mov_b32_e32 v85, v3
	v_cndmask_b32_e64 v66, 0, v66, s[22:23]
	s_nop 0
	s_waitcnt lgkmcnt(0)
	v_mfma_f32_16x16x32_f16 v[76:79], v[90:93], v[128:131], v[62:65]
	v_mov_b32_e32 v92, v3
	s_nop 2
	v_cndmask_b32_e64 v0, 0, v72, s[10:11]
	v_cndmask_b32_e64 v37, 0, v73, s[14:15]
	v_cvt_f16_f32_e32 v63, v84
	v_mfma_f32_16x16x32_f16 v[94:97], v[98:101], v[94:97], v[68:71]
	v_cndmask_b32_e64 v64, 0, v74, s[16:17]
	v_cndmask_b32_e64 v65, 0, v75, s[20:21]
	v_cndmask_b32_e64 v63, 0, v63, s[18:19]
	v_cndmask_b32_e64 v68, 0, v1, s[12:13]
	v_cndmask_b32_e64 v69, v2, 0, s[10:11]
	v_add_f32_e32 v62, v215, v0
	v_cvt_pk_f16_f32 v1, v64, v65
	v_cvt_pk_f16_f32 v0, v0, v37
	v_mov_b32_e32 v2, v3
	v_pack_b32_f16 v67, v63, v66
	v_pack_b32_f16 v66, v68, v69
	v_mov_b32_e32 v68, v3
	v_mov_b32_e32 v69, v3
	v_add_f32_e32 v63, v217, v37
	v_add_f32_e32 v64, v218, v64
	v_mfma_f32_16x16x32_f16 v[70:73], v[0:3], v[66:69], 0
	v_add_f32_e32 v65, v219, v65
	v_cvt_pk_f16_f32 v83, v64, v65
	v_cvt_pk_f16_f32 v82, v62, v63
	v_mfma_f32_16x16x32_f16 v[66:69], v[66:69], v[0:3], 0
	v_mov_b32_e32 v84, v3
	s_nop 2
	v_cvt_pk_f16_f32 v0, v70, v71
	v_mov_b32_e32 v70, v3
	v_mov_b32_e32 v71, v3
	v_cvt_pk_f16_f32 v1, v72, v73
	v_cvt_pk_f16_f32 v69, v68, v69
	v_cvt_pk_f16_f32 v68, v66, v67
	v_mfma_f32_16x16x32_f16 v[62:65], v[0:3], v[82:85], v[62:65]
	v_mad_i64_i32 v[36:37], s[28:29], v36, s91, v[126:127]
	global_store_short v[36:37], v60, off
	v_mfma_f32_16x16x32_f16 v[72:75], v[68:71], v[0:3], 0
	v_cvt_f16_f32_e32 v82, v61
	v_subrev_u32_e32 v36, 61, v80
	v_xad_u32 v37, v102, -4, v166
	v_mfma_f32_16x16x32_f16 v[66:69], v[0:3], v[68:71], 0
	s_nop 0
	v_cvt_pk_f16_f32 v71, v64, v65
	s_nop 1
	v_cvt_pk_f16_f32 v1, v74, v75
	v_cvt_pk_f16_f32 v0, v72, v73
	ds_read2_b64 v[136:139], v227 offset1:4
	v_mfma_f32_16x16x32_f16 v[56:59], v[98:101], v[128:131], v[86:89]
	v_cvt_pk_f16_f32 v70, v62, v63
	v_mov_b32_e32 v72, v3
	v_mov_b32_e32 v73, v3
	v_cvt_pk_f16_f32 v85, v68, v69
	ds_read2_b64 v[128:131], v227 offset0:8 offset1:12
	v_cvt_pk_f16_f32 v84, v66, v67
	v_mov_b32_e32 v86, v3
	v_mov_b32_e32 v87, v3
	v_mfma_f32_16x16x32_f16 v[88:91], v[0:3], v[70:73], v[62:65]
	s_nop 0
	s_nop 0
	v_cndmask_b32_e64 v36, v37, v36, s[2:3]
	v_mfma_f32_16x16x32_f16 v[60:63], v[84:87], v[0:3], 0
	v_add_u32_e32 v83, v36, v173
	s_nop 2
	v_cvt_pk_f16_f32 v1, v90, v91
	v_cvt_pk_f16_f32 v0, v88, v89
	v_cvt_pk_f16_f32 v67, v54, v55
	v_cvt_pk_f16_f32 v66, v52, v53
	v_cvt_pk_f16_f32 v85, v62, v63
	v_cvt_pk_f16_f32 v84, v60, v61
	v_cvt_pk_f16_f32 v63, v50, v51
	v_cvt_pk_f16_f32 v62, v48, v49
	v_cvt_pk_f16_f32 v61, v42, v43
	v_cvt_pk_f16_f32 v60, v40, v41
	v_cvt_pk_f16_f32 v65, v46, v47
	v_cvt_pk_f16_f32 v64, v44, v45
	s_nop 0
	s_waitcnt lgkmcnt(1)
	v_mfma_f32_16x16x32_f16 v[68:71], v[136:139], v[60:63], 0
	v_add_u32_e32 v36, 0x1000, v227
	v_mov_b32_e32 v93, v3
	v_cvt_f16_f32_e32 v76, v76
	s_nop 0
	s_waitcnt lgkmcnt(0)
	v_mfma_f32_16x16x32_f16 v[98:101], v[128:131], v[64:67], v[68:71]
	ds_read2_b64 v[72:75], v36 offset0:64 offset1:68
	s_nop 1
	ds_read2_b64 v[68:71], v36 offset0:72 offset1:76
	v_cvt_f16_f32_e32 v36, v97
	v_cvt_f16_f32_e32 v97, v77
	v_mfma_f32_16x16x32_f16 v[84:87], v[84:87], v[0:3], v[88:91]
	v_cvt_f16_f32_e32 v0, v94
	v_cvt_f16_f32_e32 v1, v95
	v_cvt_f16_f32_e32 v2, v96
	v_cndmask_b32_e64 v96, v76, 0, s[12:13]
	v_cndmask_b32_e64 v0, 0, v0, s[10:11]
	v_cndmask_b32_e64 v37, 0, v1, s[14:15]
	v_cndmask_b32_e64 v1, 0, v2, s[16:17]
	v_cndmask_b32_e64 v2, 0, v36, s[20:21]
	v_pack_b32_f16 v1, v1, v2
	v_pack_b32_f16 v0, v0, v37
	v_mov_b32_e32 v2, v3
	v_mov_b32_e32 v36, v134
	v_mov_b32_e32 v37, v135
	v_mov_b32_e32 v38, v3
	v_mov_b32_e32 v39, v3
	v_mov_b32_e32 v94, v3
	v_mov_b32_e32 v95, v3
	v_mfma_f32_16x16x32_f16 v[88:91], v[0:3], v[36:39], v[98:101]
	v_cvt_pk_f16_f32 v1, v86, v87
	v_cvt_pk_f16_f32 v0, v84, v85
	v_cvt_f16_f32_e32 v56, v56
	v_cvt_f16_f32_e32 v98, v78
	v_cvt_f16_f32_e32 v99, v79
	s_nop 2
	v_cvt_pk_f16_f32 v91, v90, v91
	v_cvt_pk_f16_f32 v90, v88, v89
	v_cndmask_b32_e64 v97, 0, v97, s[10:11]
	v_cndmask_b32_e64 v98, v98, 0, s[18:19]
	v_mfma_f32_16x16x32_f16 v[84:87], v[0:3], v[90:93], 0
	v_add_u32_e32 v2, 0x800, v236
	ds_read2_b64 v[128:131], v2 offset0:64 offset1:144
	ds_read_b128 v[76:79], v180 offset:256
	v_mov_b32_e32 v90, v3
	v_mov_b32_e32 v91, v3
	v_cndmask_b32_e64 v99, v99, 0, s[22:23]
	ds_read_b64 v[88:89], v228 offset:5120
	ds_read_b128 v[132:135], v180 offset:320
	s_nop 3
	v_cvt_pk_f16_f32 v1, v86, v87
	v_cvt_pk_f16_f32 v0, v84, v85
	s_nop 0
	s_nop 0
	s_nop 0
	v_mov_b32_e32 v2, v3
	s_nop 0
	s_waitcnt lgkmcnt(3)
	v_mov_b32_e32 v92, v128
	v_mov_b32_e32 v93, v129
	ds_read_b64 v[84:85], v229 offset:5120
	s_nop 0
	s_waitcnt lgkmcnt(3)
	v_pk_mul_f32 v[42:43], v[42:43], v[78:79]
	v_pk_mul_f32 v[40:41], v[40:41], v[76:77]
	s_nop 0
	s_nop 0
	v_mfma_f32_16x16x32_f16 v[40:43], v[92:95], v[0:3], v[40:43]
	s_nop 0
	s_waitcnt lgkmcnt(1)
	v_pk_mul_f32 v[48:49], v[48:49], v[132:133]
	v_add_u32_e32 v76, 0xc00, v236
	ds_read2_b64 v[136:139], v76 offset0:96 offset1:176
	ds_read_b128 v[140:143], v180 offset:384
	v_mfma_f32_16x16x32_f16 v[40:43], v[88:91], v[36:39], v[40:43]
	v_mov_b32_e32 v88, v130
	v_mov_b32_e32 v89, v131
	v_pk_mul_f32 v[50:51], v[50:51], v[134:135]
	v_mov_b32_e32 v86, v3
	v_mov_b32_e32 v87, v3
	s_nop 0
	v_mfma_f32_16x16x32_f16 v[48:51], v[88:91], v[0:3], v[48:51]
	ds_read_b64 v[88:89], v230 offset:5120
	s_nop 0
	s_waitcnt lgkmcnt(2)
	v_mov_b32_e32 v92, v136
	v_mfma_f32_16x16x32_f16 v[48:51], v[84:87], v[36:39], v[48:51]
	s_nop 0
	s_nop 0
	v_mov_b32_e32 v93, v137
	v_pack_b32_f16 v76, v96, v97
	v_cndmask_b32_e64 v96, v56, 0, s[12:13]
	s_nop 0
	s_waitcnt lgkmcnt(1)
	v_pk_mul_f32 v[46:47], v[46:47], v[142:143]
	v_pk_mul_f32 v[44:45], v[44:45], v[140:141]
	ds_read_b128 v[84:87], v180 offset:448
	v_cvt_f16_f32_e32 v56, v57
	v_cvt_f16_f32_e32 v57, v58
	v_mfma_f32_16x16x32_f16 v[44:47], v[92:95], v[0:3], v[44:47]
	v_cvt_f16_f32_e32 v58, v59
	v_mov_b32_e32 v92, v138
	v_mov_b32_e32 v93, v139
	s_nop 0
	s_waitcnt lgkmcnt(1)
	v_mfma_f32_16x16x32_f16 v[44:47], v[88:91], v[36:39], v[44:47]
	ds_read_b64 v[88:89], v231 offset:5120
	s_nop 0
	s_nop 0
	v_cndmask_b32_e64 v78, v57, 0, s[18:19]
	v_cndmask_b32_e64 v79, v58, 0, s[22:23]
	v_pack_b32_f16 v77, v98, v99
	s_nop 0
	s_waitcnt lgkmcnt(1)
	v_pk_mul_f32 v[52:53], v[52:53], v[84:85]
	v_cndmask_b32_e64 v84, 0, v56, s[10:11]
	v_mfma_f32_16x16x32_f16 v[56:59], v[72:75], v[60:63], 0
	v_pack_b32_f16 v61, v78, v79
	v_mov_b32_e32 v78, v3
	v_mov_b32_e32 v79, v3
	v_mfma_f32_16x16x32_f16 v[56:59], v[68:71], v[64:67], v[56:59]
	v_mul_f32_e64 v54, v54, v86
	v_mul_f32_e64 v55, v55, v87
	v_pack_b32_f16 v60, v96, v84
	v_mov_b32_e32 v62, v3
	v_mov_b32_e32 v63, v3
	v_mfma_f32_16x16x32_f16 v[52:55], v[92:95], v[0:3], v[52:55]
	v_mfma_f32_16x16x32_f16 v[56:59], v[76:79], v[0:3], v[56:59]
	v_mad_i64_i32 v[0:1], s[28:29], v83, s91, v[126:127]
	global_store_short v[0:1], v82, off
	s_nop 0
	s_waitcnt lgkmcnt(0)
	v_mfma_f32_16x16x32_f16 v[52:55], v[88:91], v[36:39], v[52:55]
	v_subrev_u32_e32 v0, 48, v80
	v_add_u32_e32 v1, 0xef, v81
	v_cndmask_b32_e64 v0, v1, v0, s[2:3]
	v_mfma_f32_16x16x32_f16 v[36:39], v[60:63], v[36:39], v[56:59]
	v_add_u32_e32 v0, v0, v173
	v_mad_i64_i32 v[0:1], s[28:29], v0, s91, v[126:127]
	s_nop 5
	v_cvt_f16_f32_e32 v2, v36
	global_store_short v[0:1], v2, off
	v_subrev_u32_e32 v0, 47, v80
	v_add_u32_e32 v1, 0xee, v81
	v_cvt_f16_f32_e32 v2, v37
	v_cndmask_b32_e64 v0, v1, v0, s[2:3]
	v_add_u32_e32 v0, v0, v173
	v_mad_i64_i32 v[0:1], s[28:29], v0, s91, v[126:127]
	global_store_short v[0:1], v2, off
	v_subrev_u32_e32 v0, 46, v80
	v_add_u32_e32 v1, 0xed, v81
	v_cvt_f16_f32_e32 v2, v38
	v_cndmask_b32_e64 v0, v1, v0, s[2:3]
	v_add_u32_e32 v0, v0, v173
	v_mad_i64_i32 v[0:1], s[28:29], v0, s91, v[126:127]
	global_store_short v[0:1], v2, off
	v_subrev_u32_e32 v0, 45, v80
	v_add_u32_e32 v1, 0xec, v81
	v_cndmask_b32_e64 v0, v1, v0, s[2:3]
	v_cvt_f16_f32_e32 v2, v39
	v_add_u32_e32 v0, v0, v173
	v_mad_i64_i32 v[0:1], s[28:29], v0, s91, v[126:127]
	s_mov_b64 s[28:29], 0
	global_store_short v[0:1], v2, off

.LBB0_462:
	s_or_b64 exec, exec, s[26:27]
	s_waitcnt lgkmcnt(0)
	s_barrier
	ds_read_b128 v[40:43], v210 offset:9216
	ds_read_b128 v[48:51], v210 offset:18496
	ds_read_b128 v[56:59], v210 offset:9280
	ds_read_b128 v[60:63], v210 offset:23040
	ds_read_b128 v[36:39], v210 offset:18432
	s_nop 0
	s_nop 0
	s_nop 0
	ds_read_b128 v[64:67], v210 offset:13824
	s_waitcnt lgkmcnt(1)
	v_mfma_f32_16x16x32_f16 v[52:55], v[40:43], v[36:39], 0
	s_nop 0
	s_nop 0
	s_nop 0
	ds_read_b128 v[68:71], v210 offset:13888
	ds_read_b128 v[72:75], v210 offset:23104
	v_add_u32_e32 v80, 0x1000, v215
	s_nop 0
	v_mfma_f32_16x16x32_f16 v[52:55], v[56:59], v[48:51], v[52:55]
	v_mov_b32_e32 v82, v3
	v_mov_b32_e32 v83, v3
	v_mov_b32_e32 v86, v3
	v_mfma_f32_16x16x32_f16 v[44:47], v[36:39], v[40:43], 0
	s_nop 3
	v_cvt_f16_f32_e32 v0, v52
	v_cvt_f16_f32_e32 v1, v54
	v_cvt_f16_f32_e32 v2, v55
	v_mfma_f32_16x16x32_f16 v[44:47], v[48:51], v[56:59], v[44:47]
	v_cndmask_b32_e64 v79, 0, v0, s[12:13]
	v_cvt_f16_f32_e32 v0, v53
	v_cndmask_b32_e64 v54, 0, v1, s[18:19]
	s_nop 0
	v_mfma_f32_16x16x32_f16 v[40:43], v[60:63], v[40:43], 0
	v_cndmask_b32_e64 v55, 0, v2, s[22:23]
	s_nop 1
	v_cndmask_b32_e64 v76, 0, v44, s[10:11]
	v_cndmask_b32_e64 v77, 0, v45, s[14:15]
	s_nop 0
	s_waitcnt lgkmcnt(2)
	v_mfma_f32_16x16x32_f16 v[36:39], v[36:39], v[64:67], 0
	v_cndmask_b32_e64 v52, 0, v46, s[16:17]
	v_cndmask_b32_e64 v78, 0, v47, s[20:21]
	v_cndmask_b32_e64 v53, v0, 0, s[10:11]
	v_mfma_f32_16x16x32_f16 v[44:47], v[60:63], v[64:67], 0
	v_cvt_pk_f16_f32 v1, v52, v78
	v_cvt_pk_f16_f32 v0, v76, v77
	v_mov_b32_e32 v2, v3
	s_nop 0
	s_waitcnt lgkmcnt(0)
	v_mfma_f32_16x16x32_f16 v[60:63], v[72:75], v[56:59], v[40:43]
	v_add_f32_e32 v56, v211, v76
	v_add_f32_e32 v57, v212, v77
	v_add_f32_e32 v58, v213, v52
	v_mfma_f32_16x16x32_f16 v[40:43], v[48:51], v[68:71], v[36:39]
	v_add_f32_e32 v59, v214, v78
	v_cvt_pk_f16_f32 v67, v18, v19
	v_cvt_pk_f16_f32 v66, v16, v17
	v_pack_b32_f16 v37, v54, v55
	v_pack_b32_f16 v36, v79, v53
	v_mov_b32_e32 v38, v3
	v_mov_b32_e32 v39, v3
	v_mfma_f32_16x16x32_f16 v[52:55], v[72:75], v[68:71], v[44:47]
	ds_read2_b64 v[68:71], v215 offset0:8 offset1:12
	v_cvt_pk_f16_f32 v65, v14, v15
	v_cvt_pk_f16_f32 v64, v12, v13
	v_mfma_f32_16x16x32_f16 v[48:51], v[0:3], v[36:39], 0
	v_cvt_pk_f16_f32 v45, v58, v59
	v_cvt_pk_f16_f32 v44, v56, v57
	v_mov_b32_e32 v46, v3
	v_mfma_f32_16x16x32_f16 v[36:39], v[36:39], v[0:3], 0
	v_mov_b32_e32 v47, v3
	s_nop 2
	v_cvt_pk_f16_f32 v1, v50, v51
	v_cvt_pk_f16_f32 v0, v48, v49
	v_mov_b32_e32 v50, v3
	v_mov_b32_e32 v51, v3
	v_cvt_pk_f16_f32 v49, v38, v39
	v_cvt_pk_f16_f32 v48, v36, v37
	v_mfma_f32_16x16x32_f16 v[44:47], v[0:3], v[44:47], v[56:59]
	v_mov_b32_e32 v87, v3
	v_mov_b32_e32 v90, v3
	v_mov_b32_e32 v91, v3
	v_mfma_f32_16x16x32_f16 v[36:39], v[48:51], v[0:3], 0
	ds_read2_b64 v[126:129], v215 offset1:4
	v_cvt_pk_f16_f32 v59, v10, v11
	v_cvt_pk_f16_f32 v58, v8, v9
	v_cvt_pk_f16_f32 v57, v6, v7
	v_mfma_f32_16x16x32_f16 v[48:51], v[0:3], v[48:51], 0
	v_cvt_pk_f16_f32 v56, v4, v5
	s_nop 2
	v_cvt_pk_f16_f32 v1, v38, v39
	v_cvt_pk_f16_f32 v0, v36, v37
	v_cvt_pk_f16_f32 v37, v46, v47
	v_cvt_pk_f16_f32 v36, v44, v45
	v_mov_b32_e32 v38, v3
	v_mov_b32_e32 v39, v3
	v_cvt_f16_f32_e32 v52, v52
	s_add_i32 s28, s76, 1
	v_mfma_f32_16x16x32_f16 v[44:47], v[0:3], v[36:39], v[44:47]
	v_cvt_pk_f16_f32 v37, v50, v51
	v_cvt_pk_f16_f32 v36, v48, v49
	v_mov_b32_e32 v50, v3
	v_mov_b32_e32 v51, v3
	v_mfma_f32_16x16x32_f16 v[36:39], v[36:39], v[0:3], 0
	s_nop 2
	v_cvt_pk_f16_f32 v1, v46, v47
	v_cvt_pk_f16_f32 v0, v44, v45
	s_nop 2
	v_cvt_pk_f16_f32 v49, v38, v39
	v_cvt_pk_f16_f32 v48, v36, v37
	s_nop 0
	s_nop 0
	s_waitcnt lgkmcnt(0)
	v_mfma_f32_16x16x32_f16 v[36:39], v[126:129], v[56:59], 0
	v_mfma_f32_16x16x32_f16 v[44:47], v[48:51], v[0:3], v[44:47]
	v_cvt_f16_f32_e32 v0, v60
	v_cvt_f16_f32_e32 v1, v61
	v_cvt_f16_f32_e32 v2, v62
	v_cvt_f16_f32_e32 v48, v63
	v_mfma_f32_16x16x32_f16 v[76:79], v[68:71], v[64:67], v[36:39]
	ds_read2_b64 v[72:75], v80 offset0:64 offset1:68
	ds_read2st64_b64 v[130:133], v216 offset0:20 offset1:25
	ds_read2_b64 v[68:71], v80 offset0:72 offset1:76
	s_nop 0
	s_nop 0
	v_cndmask_b32_e64 v0, 0, v0, s[10:11]
	v_cndmask_b32_e64 v49, 0, v1, s[14:15]
	v_cndmask_b32_e64 v1, 0, v2, s[16:17]
	v_cndmask_b32_e64 v2, 0, v48, s[20:21]
	v_pack_b32_f16 v1, v1, v2
	v_pack_b32_f16 v0, v0, v49
	v_mov_b32_e32 v2, v3
	s_nop 0
	s_waitcnt lgkmcnt(1)
	v_mov_b32_e32 v60, v130
	v_mov_b32_e32 v61, v131
	ds_read2_b64 v[126:129], v231 offset1:80
	v_mov_b32_e32 v62, v3
	v_mov_b32_e32 v63, v3
	v_cvt_f16_f32_e32 v36, v40
	ds_read_b128 v[134:137], v176
	v_cvt_f16_f32_e32 v40, v42
	v_mfma_f32_16x16x32_f16 v[48:51], v[0:3], v[60:63], v[76:79]
	v_cvt_pk_f16_f32 v1, v46, v47
	v_cvt_pk_f16_f32 v0, v44, v45
	v_cvt_f16_f32_e32 v37, v41
	v_mov_b32_e32 v78, v3
	v_mov_b32_e32 v79, v3
	s_nop 2
	v_cvt_pk_f16_f32 v77, v50, v51
	v_cvt_pk_f16_f32 v76, v48, v49
	v_cndmask_b32_e64 v88, v40, 0, s[18:19]
	v_mfma_f32_16x16x32_f16 v[56:59], v[72:75], v[56:59], 0
	v_cndmask_b32_e64 v36, v36, 0, s[12:13]
	v_cndmask_b32_e64 v37, 0, v37, s[10:11]
	v_mov_b32_e32 v74, v3
	v_mfma_f32_16x16x32_f16 v[44:47], v[0:3], v[76:79], 0
	ds_read_b64 v[76:77], v217 offset:5120
	ds_read_b128 v[138:141], v176 offset:64
	v_mov_b32_e32 v75, v3
	s_waitcnt lgkmcnt(4)
	v_mfma_f32_16x16x32_f16 v[56:59], v[68:71], v[64:67], v[56:59]
	s_nop 5
	v_cvt_pk_f16_f32 v1, v46, v47
	v_cvt_pk_f16_f32 v0, v44, v45
	s_nop 0
	s_nop 0
	s_nop 0
	s_nop 0
	s_waitcnt lgkmcnt(3)
	v_mov_b32_e32 v80, v126
	v_mov_b32_e32 v81, v127
	ds_read_b64 v[44:45], v218 offset:5120
	ds_read2_b64 v[142:145], v231 offset0:160 offset1:240
	s_nop 0
	s_waitcnt lgkmcnt(4)
	v_pk_mul_f32 v[50:51], v[6:7], v[136:137]
	v_pk_mul_f32 v[48:49], v[4:5], v[134:135]
	ds_read_b128 v[134:137], v176 offset:128
	s_nop 1
	v_mfma_f32_16x16x32_f16 v[48:51], v[80:83], v[0:3], v[48:51]
	v_cvt_f16_f32_e32 v80, v43
	v_cndmask_b32_e64 v89, v80, 0, s[22:23]
	s_nop 0
	s_waitcnt lgkmcnt(4)
	v_mfma_f32_16x16x32_f16 v[40:43], v[76:79], v[60:63], v[48:51]
	s_nop 3
	s_nop 0
	s_nop 0
	ds_read_b64 v[80:81], v219 offset:5120
	v_mov_b32_e32 v76, v128
	v_mov_b32_e32 v77, v129
	v_mov_b32_e32 v46, v3
	s_nop 0
	s_waitcnt lgkmcnt(4)
	v_pk_mul_f32 v[50:51], v[10:11], v[140:141]
	v_pk_mul_f32 v[48:49], v[8:9], v[138:139]
	v_mov_b32_e32 v47, v3
	ds_read_b128 v[126:129], v176 offset:192
	s_nop 0
	v_mfma_f32_16x16x32_f16 v[48:51], v[76:79], v[0:3], v[48:51]
	s_nop 0
	s_nop 0
	s_waitcnt lgkmcnt(3)
	v_mov_b32_e32 v84, v142
	v_mfma_f32_16x16x32_f16 v[48:51], v[44:47], v[60:63], v[48:51]
	s_nop 0
	s_nop 0
	v_mov_b32_e32 v85, v143
	v_pack_b32_f16 v77, v88, v89
	v_mov_b32_e32 v88, v144
	s_nop 0
	s_waitcnt lgkmcnt(2)
	v_pk_mul_f32 v[46:47], v[14:15], v[136:137]
	v_pk_mul_f32 v[44:45], v[12:13], v[134:135]
	v_mov_b32_e32 v89, v145
	v_pack_b32_f16 v76, v36, v37
	v_mfma_f32_16x16x32_f16 v[44:47], v[84:87], v[0:3], v[44:47]
	ds_read_b64 v[84:85], v220 offset:5120
	v_cndmask_b32_e64 v36, v52, 0, s[12:13]
	v_cvt_f16_f32_e32 v37, v53
	v_cndmask_b32_e64 v37, 0, v37, s[10:11]
	s_nop 0
	s_waitcnt lgkmcnt(2)
	v_mfma_f32_16x16x32_f16 v[44:47], v[80:83], v[60:63], v[44:47]
	s_nop 0
	s_nop 0
	v_pack_b32_f16 v72, v36, v37
	ds_read_b128 v[68:71], v221 offset:9216
	ds_read_b128 v[94:97], v221 offset:9280
	s_nop 0
	s_waitcnt lgkmcnt(3)
	v_pk_mul_f32 v[82:83], v[18:19], v[128:129]
	ds_read_b128 v[64:67], v221 offset:18432
	v_pk_mul_f32 v[80:81], v[16:17], v[126:127]
	s_nop 0
	ds_read_b128 v[98:101], v221 offset:23104
	v_mfma_f32_16x16x32_f16 v[78:81], v[88:91], v[0:3], v[80:83]
	ds_read_b128 v[90:93], v221 offset:18496
	s_nop 1
	v_cvt_f16_f32_e32 v82, v54
	v_cvt_f16_f32_e32 v83, v55
	s_nop 0
	s_waitcnt lgkmcnt(5)
	v_mfma_f32_16x16x32_f16 v[52:55], v[84:87], v[60:63], v[78:81]
	ds_read_b128 v[86:89], v221 offset:13824
	s_nop 1
	v_cndmask_b32_e64 v78, v82, 0, s[18:19]
	v_cndmask_b32_e64 v79, v83, 0, s[22:23]
	v_pack_b32_f16 v73, v78, v79
	v_mov_b32_e32 v78, v3
	v_mov_b32_e32 v79, v3
	v_add_u32_e32 v80, s71, v153
	v_add_u32_e32 v81, s70, v230
	v_mfma_f32_16x16x32_f16 v[56:59], v[76:79], v[0:3], v[56:59]
	ds_read_b128 v[76:79], v221 offset:23040
	v_subrev_u32_e32 v102, 64, v80
	v_add_u32_e32 v0, 0x7ff, v81
	v_mfma_f32_16x16x32_f16 v[58:61], v[72:75], v[60:63], v[56:59]
	v_cndmask_b32_e64 v0, v0, v102, s[2:3]
	v_add_u32_e32 v0, v0, v151
	v_mad_i64_i32 v[0:1], s[26:27], v0, s91, v[122:123]
	s_nop 0
	s_waitcnt lgkmcnt(4)
	v_mfma_f32_16x16x32_f16 v[82:85], v[68:71], v[64:67], 0
	s_nop 2
	v_cvt_f16_f32_e32 v2, v58
	v_cvt_f16_f32_e32 v60, v60
	ds_read_b128 v[126:129], v221 offset:13888
	global_store_short v[0:1], v2, off
	v_subrev_u32_e32 v0, 63, v80
	v_xad_u32 v1, v102, -2, v170
	v_cvt_f16_f32_e32 v2, v59
	s_nop 0
	v_mfma_f32_16x16x32_f16 v[72:75], v[64:67], v[68:71], 0
	v_cndmask_b32_e64 v0, v1, v0, s[2:3]
	v_add_u32_e32 v0, v0, v151
	v_mad_i64_i32 v[0:1], s[26:27], v0, s91, v[122:123]
	s_nop 0
	s_waitcnt lgkmcnt(2)
	v_mfma_f32_16x16x32_f16 v[62:65], v[64:67], v[86:89], 0
	global_store_short v[0:1], v2, off
	v_subrev_u32_e32 v0, 62, v80
	v_xad_u32 v1, v102, -3, v170
	v_mfma_f32_16x16x32_f16 v[82:85], v[94:97], v[90:93], v[82:85]
	v_cndmask_b32_e64 v36, v1, v0, s[2:3]
	v_add_u32_e32 v36, v36, v151
	s_nop 0
	s_waitcnt lgkmcnt(1)
	v_mfma_f32_16x16x32_f16 v[68:71], v[76:79], v[68:71], 0
	v_mfma_f32_16x16x32_f16 v[86:89], v[76:79], v[86:89], 0
	s_nop 2
	v_cvt_f16_f32_e32 v1, v82
	v_cvt_f16_f32_e32 v2, v83
	v_cvt_f16_f32_e32 v66, v85
	v_mfma_f32_16x16x32_f16 v[72:75], v[90:93], v[94:97], v[72:75]
	v_mov_b32_e32 v85, v3
	v_cndmask_b32_e64 v66, 0, v66, s[22:23]
	s_nop 0
	s_waitcnt lgkmcnt(0)
	v_mfma_f32_16x16x32_f16 v[76:79], v[90:93], v[126:129], v[62:65]
	v_mov_b32_e32 v92, v3
	s_nop 2
	v_cndmask_b32_e64 v0, 0, v72, s[10:11]
	v_cndmask_b32_e64 v37, 0, v73, s[14:15]
	v_cvt_f16_f32_e32 v63, v84
	v_mfma_f32_16x16x32_f16 v[94:97], v[98:101], v[94:97], v[68:71]
	v_cndmask_b32_e64 v64, 0, v74, s[16:17]
	v_cndmask_b32_e64 v65, 0, v75, s[20:21]
	v_cndmask_b32_e64 v63, 0, v63, s[18:19]
	v_cndmask_b32_e64 v68, 0, v1, s[12:13]
	v_cndmask_b32_e64 v69, v2, 0, s[10:11]
	v_add_f32_e32 v62, v211, v0
	v_cvt_pk_f16_f32 v1, v64, v65
	v_cvt_pk_f16_f32 v0, v0, v37
	v_mov_b32_e32 v2, v3
	v_pack_b32_f16 v67, v63, v66
	v_pack_b32_f16 v66, v68, v69
	v_mov_b32_e32 v68, v3
	v_mov_b32_e32 v69, v3
	v_add_f32_e32 v63, v212, v37
	v_add_f32_e32 v64, v213, v64
	v_mfma_f32_16x16x32_f16 v[70:73], v[0:3], v[66:69], 0
	v_add_f32_e32 v65, v214, v65
	v_cvt_pk_f16_f32 v83, v64, v65
	v_cvt_pk_f16_f32 v82, v62, v63
	v_mfma_f32_16x16x32_f16 v[66:69], v[66:69], v[0:3], 0
	v_mov_b32_e32 v84, v3
	s_nop 2
	v_cvt_pk_f16_f32 v0, v70, v71
	v_mov_b32_e32 v70, v3
	v_mov_b32_e32 v71, v3
	v_cvt_pk_f16_f32 v1, v72, v73
	v_cvt_pk_f16_f32 v69, v68, v69
	v_cvt_pk_f16_f32 v68, v66, v67
	v_mfma_f32_16x16x32_f16 v[62:65], v[0:3], v[82:85], v[62:65]
	v_mad_i64_i32 v[36:37], s[26:27], v36, s91, v[122:123]
	global_store_short v[36:37], v60, off
	v_mfma_f32_16x16x32_f16 v[72:75], v[68:71], v[0:3], 0
	v_cvt_f16_f32_e32 v82, v61
	v_subrev_u32_e32 v36, 61, v80
	v_xad_u32 v37, v102, -4, v170
	v_mfma_f32_16x16x32_f16 v[66:69], v[0:3], v[68:71], 0
	s_nop 0
	v_cvt_pk_f16_f32 v71, v64, v65
	s_nop 1
	v_cvt_pk_f16_f32 v1, v74, v75
	v_cvt_pk_f16_f32 v0, v72, v73
	ds_read2_b64 v[134:137], v222 offset1:4
	v_mfma_f32_16x16x32_f16 v[56:59], v[98:101], v[126:129], v[86:89]
	v_cvt_pk_f16_f32 v70, v62, v63
	v_mov_b32_e32 v72, v3
	v_mov_b32_e32 v73, v3
	v_cvt_pk_f16_f32 v85, v68, v69
	ds_read2_b64 v[126:129], v222 offset0:8 offset1:12
	v_cvt_pk_f16_f32 v84, v66, v67
	v_mov_b32_e32 v86, v3
	v_mov_b32_e32 v87, v3
	v_mfma_f32_16x16x32_f16 v[88:91], v[0:3], v[70:73], v[62:65]
	s_nop 0
	s_nop 0
	v_cndmask_b32_e64 v36, v37, v36, s[2:3]
	v_mfma_f32_16x16x32_f16 v[60:63], v[84:87], v[0:3], 0
	v_add_u32_e32 v83, v36, v151
	s_nop 2
	v_cvt_pk_f16_f32 v1, v90, v91
	v_cvt_pk_f16_f32 v0, v88, v89
	v_cvt_pk_f16_f32 v67, v54, v55
	v_cvt_pk_f16_f32 v66, v52, v53
	v_cvt_pk_f16_f32 v85, v62, v63
	v_cvt_pk_f16_f32 v84, v60, v61
	v_cvt_pk_f16_f32 v63, v50, v51
	v_cvt_pk_f16_f32 v62, v48, v49
	v_cvt_pk_f16_f32 v61, v42, v43
	v_cvt_pk_f16_f32 v60, v40, v41
	v_cvt_pk_f16_f32 v65, v46, v47
	v_cvt_pk_f16_f32 v64, v44, v45
	s_nop 0
	s_waitcnt lgkmcnt(1)
	v_mfma_f32_16x16x32_f16 v[68:71], v[134:137], v[60:63], 0
	v_add_u32_e32 v36, 0x1000, v222
	v_mov_b32_e32 v93, v3
	v_cvt_f16_f32_e32 v76, v76
	s_nop 0
	s_waitcnt lgkmcnt(0)
	v_mfma_f32_16x16x32_f16 v[98:101], v[126:129], v[64:67], v[68:71]
	ds_read2_b64 v[72:75], v36 offset0:64 offset1:68
	s_nop 1
	ds_read2_b64 v[68:71], v36 offset0:72 offset1:76
	v_cvt_f16_f32_e32 v36, v97
	v_cvt_f16_f32_e32 v97, v77
	v_mfma_f32_16x16x32_f16 v[84:87], v[84:87], v[0:3], v[88:91]
	v_cvt_f16_f32_e32 v0, v94
	v_cvt_f16_f32_e32 v1, v95
	v_cvt_f16_f32_e32 v2, v96
	v_cndmask_b32_e64 v96, v76, 0, s[12:13]
	v_cndmask_b32_e64 v0, 0, v0, s[10:11]
	v_cndmask_b32_e64 v37, 0, v1, s[14:15]
	v_cndmask_b32_e64 v1, 0, v2, s[16:17]
	v_cndmask_b32_e64 v2, 0, v36, s[20:21]
	v_pack_b32_f16 v1, v1, v2
	v_pack_b32_f16 v0, v0, v37
	v_mov_b32_e32 v2, v3
	v_mov_b32_e32 v36, v132
	v_mov_b32_e32 v37, v133
	v_mov_b32_e32 v38, v3
	v_mov_b32_e32 v39, v3
	v_mov_b32_e32 v94, v3
	v_mov_b32_e32 v95, v3
	v_mfma_f32_16x16x32_f16 v[88:91], v[0:3], v[36:39], v[98:101]
	v_cvt_pk_f16_f32 v1, v86, v87
	v_cvt_pk_f16_f32 v0, v84, v85
	v_cvt_f16_f32_e32 v56, v56
	v_cvt_f16_f32_e32 v98, v78
	v_cvt_f16_f32_e32 v99, v79
	s_nop 2
	v_cvt_pk_f16_f32 v91, v90, v91
	v_cvt_pk_f16_f32 v90, v88, v89
	v_cndmask_b32_e64 v97, 0, v97, s[10:11]
	v_cndmask_b32_e64 v98, v98, 0, s[18:19]
	v_mfma_f32_16x16x32_f16 v[84:87], v[0:3], v[90:93], 0
	v_add_u32_e32 v2, 0x800, v231
	ds_read2_b64 v[126:129], v2 offset0:64 offset1:144
	ds_read_b128 v[76:79], v176 offset:256
	v_mov_b32_e32 v90, v3
	v_mov_b32_e32 v91, v3
	v_cndmask_b32_e64 v99, v99, 0, s[22:23]
	ds_read_b64 v[88:89], v223 offset:5120
	ds_read_b128 v[130:133], v176 offset:320
	s_nop 3
	v_cvt_pk_f16_f32 v1, v86, v87
	v_cvt_pk_f16_f32 v0, v84, v85
	s_nop 0
	s_nop 0
	s_nop 0
	v_mov_b32_e32 v2, v3
	s_nop 0
	s_waitcnt lgkmcnt(3)
	v_mov_b32_e32 v92, v126
	v_mov_b32_e32 v93, v127
	ds_read_b64 v[84:85], v224 offset:5120
	s_nop 0
	s_waitcnt lgkmcnt(3)
	v_pk_mul_f32 v[42:43], v[42:43], v[78:79]
	v_pk_mul_f32 v[40:41], v[40:41], v[76:77]
	s_nop 0
	s_nop 0
	v_mfma_f32_16x16x32_f16 v[40:43], v[92:95], v[0:3], v[40:43]
	s_nop 0
	s_waitcnt lgkmcnt(1)
	v_pk_mul_f32 v[48:49], v[48:49], v[130:131]
	v_add_u32_e32 v76, 0xc00, v231
	ds_read2_b64 v[134:137], v76 offset0:96 offset1:176
	ds_read_b128 v[138:141], v176 offset:384
	v_mfma_f32_16x16x32_f16 v[40:43], v[88:91], v[36:39], v[40:43]
	v_mov_b32_e32 v88, v128
	v_mov_b32_e32 v89, v129
	v_pk_mul_f32 v[50:51], v[50:51], v[132:133]
	v_mov_b32_e32 v86, v3
	v_mov_b32_e32 v87, v3
	s_nop 0
	v_mfma_f32_16x16x32_f16 v[48:51], v[88:91], v[0:3], v[48:51]
	ds_read_b64 v[88:89], v225 offset:5120
	s_nop 0
	s_waitcnt lgkmcnt(2)
	v_mov_b32_e32 v92, v134
	v_mfma_f32_16x16x32_f16 v[48:51], v[84:87], v[36:39], v[48:51]
	s_nop 0
	s_nop 0
	v_mov_b32_e32 v93, v135
	v_pack_b32_f16 v76, v96, v97
	v_cndmask_b32_e64 v96, v56, 0, s[12:13]
	s_nop 0
	s_waitcnt lgkmcnt(1)
	v_pk_mul_f32 v[46:47], v[46:47], v[140:141]
	v_pk_mul_f32 v[44:45], v[44:45], v[138:139]
	ds_read_b128 v[84:87], v176 offset:448
	v_cvt_f16_f32_e32 v56, v57
	v_cvt_f16_f32_e32 v57, v58
	v_mfma_f32_16x16x32_f16 v[44:47], v[92:95], v[0:3], v[44:47]
	v_cvt_f16_f32_e32 v58, v59
	v_mov_b32_e32 v92, v136
	v_mov_b32_e32 v93, v137
	s_nop 0
	s_waitcnt lgkmcnt(1)
	v_mfma_f32_16x16x32_f16 v[44:47], v[88:91], v[36:39], v[44:47]
	ds_read_b64 v[88:89], v226 offset:5120
	s_nop 0
	s_nop 0
	v_cndmask_b32_e64 v78, v57, 0, s[18:19]
	v_cndmask_b32_e64 v79, v58, 0, s[22:23]
	v_pack_b32_f16 v77, v98, v99
	s_nop 0
	s_waitcnt lgkmcnt(1)
	v_pk_mul_f32 v[52:53], v[52:53], v[84:85]
	v_cndmask_b32_e64 v84, 0, v56, s[10:11]
	v_mfma_f32_16x16x32_f16 v[56:59], v[72:75], v[60:63], 0
	v_pack_b32_f16 v61, v78, v79
	v_mov_b32_e32 v78, v3
	v_mov_b32_e32 v79, v3
	v_mfma_f32_16x16x32_f16 v[56:59], v[68:71], v[64:67], v[56:59]
	v_mul_f32_e64 v54, v54, v86
	v_mul_f32_e64 v55, v55, v87
	v_pack_b32_f16 v60, v96, v84
	v_mov_b32_e32 v62, v3
	v_mov_b32_e32 v63, v3
	v_mfma_f32_16x16x32_f16 v[52:55], v[92:95], v[0:3], v[52:55]
	v_mfma_f32_16x16x32_f16 v[56:59], v[76:79], v[0:3], v[56:59]
	v_mad_i64_i32 v[0:1], s[26:27], v83, s91, v[122:123]
	global_store_short v[0:1], v82, off
	s_nop 0
	s_waitcnt lgkmcnt(0)
	v_mfma_f32_16x16x32_f16 v[52:55], v[88:91], v[36:39], v[52:55]
	v_subrev_u32_e32 v0, 48, v80
	v_add_u32_e32 v1, 0x7ef, v81
	v_cndmask_b32_e64 v0, v1, v0, s[2:3]
	v_mfma_f32_16x16x32_f16 v[36:39], v[60:63], v[36:39], v[56:59]
	v_add_u32_e32 v0, v0, v151
	v_mad_i64_i32 v[0:1], s[26:27], v0, s91, v[122:123]
	s_nop 5
	v_cvt_f16_f32_e32 v2, v36
	global_store_short v[0:1], v2, off
	v_subrev_u32_e32 v0, 47, v80
	v_add_u32_e32 v1, 0x7ee, v81
	v_cvt_f16_f32_e32 v2, v37
	v_cndmask_b32_e64 v0, v1, v0, s[2:3]
	v_add_u32_e32 v0, v0, v151
	v_mad_i64_i32 v[0:1], s[26:27], v0, s91, v[122:123]
	global_store_short v[0:1], v2, off
	v_subrev_u32_e32 v0, 46, v80
	v_add_u32_e32 v1, 0x7ed, v81
	v_cvt_f16_f32_e32 v2, v38
	v_cndmask_b32_e64 v0, v1, v0, s[2:3]
	v_add_u32_e32 v0, v0, v151
	v_mad_i64_i32 v[0:1], s[26:27], v0, s91, v[122:123]
	global_store_short v[0:1], v2, off
	v_subrev_u32_e32 v0, 45, v80
	v_add_u32_e32 v1, 0x7ec, v81
	v_cndmask_b32_e64 v0, v1, v0, s[2:3]
	v_cvt_f16_f32_e32 v2, v39
	v_add_u32_e32 v0, v0, v151
	v_mad_i64_i32 v[0:1], s[26:27], v0, s91, v[122:123]
	s_mov_b64 s[26:27], 0
	global_store_short v[0:1], v2, off

.LBB0_935:
	s_or_b64 exec, exec, s[28:29]
	s_waitcnt lgkmcnt(0)
	s_barrier
	ds_read_b128 v[40:43], v216 offset:9216
	ds_read_b128 v[48:51], v216 offset:18496
	ds_read_b128 v[56:59], v216 offset:9280
	ds_read_b128 v[60:63], v216 offset:23040
	ds_read_b128 v[36:39], v216 offset:18432
	s_nop 0
	s_nop 0
	s_nop 0
	ds_read_b128 v[64:67], v216 offset:13824
	s_waitcnt lgkmcnt(1)
	v_mfma_f32_16x16x32_f16 v[52:55], v[40:43], v[36:39], 0
	s_nop 0
	s_nop 0
	s_nop 0
	ds_read_b128 v[68:71], v216 offset:13888
	ds_read_b128 v[72:75], v216 offset:23104
	v_add_u32_e32 v80, 0x1000, v222
	s_nop 0
	v_mfma_f32_16x16x32_f16 v[52:55], v[56:59], v[48:51], v[52:55]
	v_mov_b32_e32 v82, v3
	v_mov_b32_e32 v83, v3
	v_mov_b32_e32 v86, v3
	v_mfma_f32_16x16x32_f16 v[44:47], v[36:39], v[40:43], 0
	s_nop 3
	v_cvt_f16_f32_e32 v0, v52
	v_cvt_f16_f32_e32 v1, v54
	v_cvt_f16_f32_e32 v2, v55
	v_mfma_f32_16x16x32_f16 v[44:47], v[48:51], v[56:59], v[44:47]
	v_cndmask_b32_e64 v79, 0, v0, s[12:13]
	v_cvt_f16_f32_e32 v0, v53
	v_cndmask_b32_e64 v54, 0, v1, s[18:19]
	s_nop 0
	v_mfma_f32_16x16x32_f16 v[40:43], v[60:63], v[40:43], 0
	v_cndmask_b32_e64 v55, 0, v2, s[22:23]
	s_nop 1
	v_cndmask_b32_e64 v76, 0, v44, s[10:11]
	v_cndmask_b32_e64 v77, 0, v45, s[14:15]
	s_nop 0
	s_waitcnt lgkmcnt(2)
	v_mfma_f32_16x16x32_f16 v[36:39], v[36:39], v[64:67], 0
	v_cndmask_b32_e64 v52, 0, v46, s[16:17]
	v_cndmask_b32_e64 v78, 0, v47, s[20:21]
	v_cndmask_b32_e64 v53, v0, 0, s[10:11]
	v_mfma_f32_16x16x32_f16 v[44:47], v[60:63], v[64:67], 0
	v_cvt_pk_f16_f32 v1, v52, v78
	v_cvt_pk_f16_f32 v0, v76, v77
	v_mov_b32_e32 v2, v3
	s_nop 0
	s_waitcnt lgkmcnt(0)
	v_mfma_f32_16x16x32_f16 v[60:63], v[72:75], v[56:59], v[40:43]
	v_add_f32_e32 v56, v217, v76
	v_add_f32_e32 v57, v219, v77
	v_add_f32_e32 v58, v220, v52
	v_mfma_f32_16x16x32_f16 v[40:43], v[48:51], v[68:71], v[36:39]
	v_add_f32_e32 v59, v221, v78
	v_cvt_pk_f16_f32 v67, v26, v27
	v_cvt_pk_f16_f32 v66, v24, v25
	v_pack_b32_f16 v37, v54, v55
	v_pack_b32_f16 v36, v79, v53
	v_mov_b32_e32 v38, v3
	v_mov_b32_e32 v39, v3
	v_mfma_f32_16x16x32_f16 v[52:55], v[72:75], v[68:71], v[44:47]
	ds_read2_b64 v[68:71], v222 offset0:8 offset1:12
	v_cvt_pk_f16_f32 v65, v30, v31
	v_cvt_pk_f16_f32 v64, v28, v29
	v_mfma_f32_16x16x32_f16 v[48:51], v[0:3], v[36:39], 0
	v_cvt_pk_f16_f32 v45, v58, v59
	v_cvt_pk_f16_f32 v44, v56, v57
	v_mov_b32_e32 v46, v3
	v_mfma_f32_16x16x32_f16 v[36:39], v[36:39], v[0:3], 0
	v_mov_b32_e32 v47, v3
	s_nop 2
	v_cvt_pk_f16_f32 v1, v50, v51
	v_cvt_pk_f16_f32 v0, v48, v49
	v_mov_b32_e32 v50, v3
	v_mov_b32_e32 v51, v3
	v_cvt_pk_f16_f32 v49, v38, v39
	v_cvt_pk_f16_f32 v48, v36, v37
	v_mfma_f32_16x16x32_f16 v[44:47], v[0:3], v[44:47], v[56:59]
	v_mov_b32_e32 v87, v3
	v_mov_b32_e32 v90, v3
	v_mov_b32_e32 v91, v3
	v_mfma_f32_16x16x32_f16 v[36:39], v[48:51], v[0:3], 0
	ds_read2_b64 v[128:131], v222 offset1:4
	v_cvt_pk_f16_f32 v59, v34, v35
	v_cvt_pk_f16_f32 v58, v32, v33
	v_cvt_pk_f16_f32 v57, v22, v23
	v_mfma_f32_16x16x32_f16 v[48:51], v[0:3], v[48:51], 0
	v_cvt_pk_f16_f32 v56, v20, v21
	s_nop 2
	v_cvt_pk_f16_f32 v1, v38, v39
	v_cvt_pk_f16_f32 v0, v36, v37
	v_cvt_pk_f16_f32 v37, v46, v47
	v_cvt_pk_f16_f32 v36, v44, v45
	v_mov_b32_e32 v38, v3
	v_mov_b32_e32 v39, v3
	v_cvt_f16_f32_e32 v52, v52
	s_add_i32 s27, s26, 1
	v_mfma_f32_16x16x32_f16 v[44:47], v[0:3], v[36:39], v[44:47]
	v_cvt_pk_f16_f32 v37, v50, v51
	v_cvt_pk_f16_f32 v36, v48, v49
	v_mov_b32_e32 v50, v3
	v_mov_b32_e32 v51, v3
	v_mfma_f32_16x16x32_f16 v[36:39], v[36:39], v[0:3], 0
	s_nop 2
	v_cvt_pk_f16_f32 v1, v46, v47
	v_cvt_pk_f16_f32 v0, v44, v45
	s_nop 2
	v_cvt_pk_f16_f32 v49, v38, v39
	v_cvt_pk_f16_f32 v48, v36, v37
	s_nop 0
	s_nop 0
	s_waitcnt lgkmcnt(0)
	v_mfma_f32_16x16x32_f16 v[36:39], v[128:131], v[56:59], 0
	v_mfma_f32_16x16x32_f16 v[44:47], v[48:51], v[0:3], v[44:47]
	v_cvt_f16_f32_e32 v0, v60
	v_cvt_f16_f32_e32 v1, v61
	v_cvt_f16_f32_e32 v2, v62
	v_cvt_f16_f32_e32 v48, v63
	v_mfma_f32_16x16x32_f16 v[76:79], v[68:71], v[64:67], v[36:39]
	ds_read2_b64 v[72:75], v80 offset0:64 offset1:68
	ds_read2st64_b64 v[132:135], v223 offset0:20 offset1:25
	ds_read2_b64 v[68:71], v80 offset0:72 offset1:76
	s_nop 0
	s_nop 0
	v_cndmask_b32_e64 v0, 0, v0, s[10:11]
	v_cndmask_b32_e64 v49, 0, v1, s[14:15]
	v_cndmask_b32_e64 v1, 0, v2, s[16:17]
	v_cndmask_b32_e64 v2, 0, v48, s[20:21]
	v_pack_b32_f16 v1, v1, v2
	v_pack_b32_f16 v0, v0, v49
	v_mov_b32_e32 v2, v3
	s_nop 0
	s_waitcnt lgkmcnt(1)
	v_mov_b32_e32 v60, v132
	v_mov_b32_e32 v61, v133
	ds_read2_b64 v[128:131], v240 offset1:80
	v_mov_b32_e32 v62, v3
	v_mov_b32_e32 v63, v3
	v_cvt_f16_f32_e32 v36, v40
	ds_read_b128 v[136:139], v182
	v_cvt_f16_f32_e32 v40, v42
	v_mfma_f32_16x16x32_f16 v[48:51], v[0:3], v[60:63], v[76:79]
	v_cvt_pk_f16_f32 v1, v46, v47
	v_cvt_pk_f16_f32 v0, v44, v45
	v_cvt_f16_f32_e32 v37, v41
	v_mov_b32_e32 v78, v3
	v_mov_b32_e32 v79, v3
	s_nop 2
	v_cvt_pk_f16_f32 v77, v50, v51
	v_cvt_pk_f16_f32 v76, v48, v49
	v_cndmask_b32_e64 v88, v40, 0, s[18:19]
	v_mfma_f32_16x16x32_f16 v[56:59], v[72:75], v[56:59], 0
	v_cndmask_b32_e64 v36, v36, 0, s[12:13]
	v_cndmask_b32_e64 v37, 0, v37, s[10:11]
	v_mov_b32_e32 v74, v3
	v_mfma_f32_16x16x32_f16 v[44:47], v[0:3], v[76:79], 0
	ds_read_b64 v[76:77], v224 offset:5120
	ds_read_b128 v[140:143], v182 offset:64
	v_mov_b32_e32 v75, v3
	s_waitcnt lgkmcnt(4)
	v_mfma_f32_16x16x32_f16 v[56:59], v[68:71], v[64:67], v[56:59]
	s_nop 5
	v_cvt_pk_f16_f32 v1, v46, v47
	v_cvt_pk_f16_f32 v0, v44, v45
	s_nop 0
	s_nop 0
	s_nop 0
	s_nop 0
	s_waitcnt lgkmcnt(3)
	v_mov_b32_e32 v80, v128
	v_mov_b32_e32 v81, v129
	ds_read_b64 v[44:45], v225 offset:5120
	ds_read2_b64 v[144:147], v240 offset0:160 offset1:240
	s_nop 0
	s_waitcnt lgkmcnt(4)
	v_pk_mul_f32 v[50:51], v[22:23], v[138:139]
	v_pk_mul_f32 v[48:49], v[20:21], v[136:137]
	ds_read_b128 v[136:139], v182 offset:128
	s_nop 1
	v_mfma_f32_16x16x32_f16 v[48:51], v[80:83], v[0:3], v[48:51]
	v_cvt_f16_f32_e32 v80, v43
	v_cndmask_b32_e64 v89, v80, 0, s[22:23]
	s_nop 0
	s_waitcnt lgkmcnt(4)
	v_mfma_f32_16x16x32_f16 v[40:43], v[76:79], v[60:63], v[48:51]
	s_nop 3
	s_nop 0
	s_nop 0
	ds_read_b64 v[80:81], v226 offset:5120
	v_mov_b32_e32 v76, v130
	v_mov_b32_e32 v77, v131
	v_mov_b32_e32 v46, v3
	s_nop 0
	s_waitcnt lgkmcnt(4)
	v_pk_mul_f32 v[50:51], v[34:35], v[142:143]
	v_pk_mul_f32 v[48:49], v[32:33], v[140:141]
	v_mov_b32_e32 v47, v3
	ds_read_b128 v[128:131], v182 offset:192
	s_nop 0
	v_mfma_f32_16x16x32_f16 v[48:51], v[76:79], v[0:3], v[48:51]
	s_nop 0
	s_nop 0
	s_waitcnt lgkmcnt(3)
	v_mov_b32_e32 v84, v144
	v_mfma_f32_16x16x32_f16 v[48:51], v[44:47], v[60:63], v[48:51]
	s_nop 0
	s_nop 0
	v_mov_b32_e32 v85, v145
	v_pack_b32_f16 v77, v88, v89
	v_mov_b32_e32 v88, v146
	s_nop 0
	s_waitcnt lgkmcnt(2)
	v_pk_mul_f32 v[46:47], v[30:31], v[138:139]
	v_pk_mul_f32 v[44:45], v[28:29], v[136:137]
	v_mov_b32_e32 v89, v147
	v_pack_b32_f16 v76, v36, v37
	v_mfma_f32_16x16x32_f16 v[44:47], v[84:87], v[0:3], v[44:47]
	ds_read_b64 v[84:85], v227 offset:5120
	v_cndmask_b32_e64 v36, v52, 0, s[12:13]
	v_cvt_f16_f32_e32 v37, v53
	v_cndmask_b32_e64 v37, 0, v37, s[10:11]
	s_nop 0
	s_waitcnt lgkmcnt(2)
	v_mfma_f32_16x16x32_f16 v[44:47], v[80:83], v[60:63], v[44:47]
	s_nop 0
	s_nop 0
	v_pack_b32_f16 v72, v36, v37
	ds_read_b128 v[68:71], v228 offset:9216
	ds_read_b128 v[94:97], v228 offset:9280
	s_nop 0
	s_waitcnt lgkmcnt(3)
	v_pk_mul_f32 v[82:83], v[26:27], v[130:131]
	ds_read_b128 v[64:67], v228 offset:18432
	v_pk_mul_f32 v[80:81], v[24:25], v[128:129]
	s_nop 0
	ds_read_b128 v[98:101], v228 offset:23104
	v_mfma_f32_16x16x32_f16 v[78:81], v[88:91], v[0:3], v[80:83]
	ds_read_b128 v[90:93], v228 offset:18496
	s_nop 1
	v_cvt_f16_f32_e32 v82, v54
	v_cvt_f16_f32_e32 v83, v55
	s_nop 0
	s_waitcnt lgkmcnt(5)
	v_mfma_f32_16x16x32_f16 v[52:55], v[84:87], v[60:63], v[78:81]
	ds_read_b128 v[86:89], v228 offset:13824
	s_nop 1
	v_cndmask_b32_e64 v78, v82, 0, s[18:19]
	v_cndmask_b32_e64 v79, v83, 0, s[22:23]
	v_pack_b32_f16 v73, v78, v79
	v_mov_b32_e32 v78, v3
	v_mov_b32_e32 v79, v3
	v_add_u32_e32 v80, s77, v122
	v_add_u32_e32 v81, s76, v237
	v_mfma_f32_16x16x32_f16 v[56:59], v[76:79], v[0:3], v[56:59]
	ds_read_b128 v[76:79], v228 offset:23040
	v_subrev_u32_e32 v102, 64, v80
	v_add_u32_e32 v0, 0xff, v81
	v_mfma_f32_16x16x32_f16 v[58:61], v[72:75], v[60:63], v[56:59]
	v_cndmask_b32_e64 v0, v0, v102, s[2:3]
	v_add_u32_e32 v0, v0, v175
	v_mad_i64_i32 v[0:1], s[28:29], v0, s88, v[126:127]
	s_nop 0
	s_waitcnt lgkmcnt(4)
	v_mfma_f32_16x16x32_f16 v[82:85], v[68:71], v[64:67], 0
	s_nop 2
	v_cvt_f16_f32_e32 v2, v58
	v_cvt_f16_f32_e32 v60, v60
	ds_read_b128 v[128:131], v228 offset:13888
	global_store_short v[0:1], v2, off
	v_subrev_u32_e32 v0, 63, v80
	v_xad_u32 v1, v102, -2, v168
	v_cvt_f16_f32_e32 v2, v59
	s_nop 0
	v_mfma_f32_16x16x32_f16 v[72:75], v[64:67], v[68:71], 0
	v_cndmask_b32_e64 v0, v1, v0, s[2:3]
	v_add_u32_e32 v0, v0, v175
	v_mad_i64_i32 v[0:1], s[28:29], v0, s88, v[126:127]
	s_nop 0
	s_waitcnt lgkmcnt(2)
	v_mfma_f32_16x16x32_f16 v[62:65], v[64:67], v[86:89], 0
	global_store_short v[0:1], v2, off
	v_subrev_u32_e32 v0, 62, v80
	v_xad_u32 v1, v102, -3, v168
	v_mfma_f32_16x16x32_f16 v[82:85], v[94:97], v[90:93], v[82:85]
	v_cndmask_b32_e64 v36, v1, v0, s[2:3]
	v_add_u32_e32 v36, v36, v175
	s_nop 0
	s_waitcnt lgkmcnt(1)
	v_mfma_f32_16x16x32_f16 v[68:71], v[76:79], v[68:71], 0
	v_mfma_f32_16x16x32_f16 v[86:89], v[76:79], v[86:89], 0
	s_nop 2
	v_cvt_f16_f32_e32 v1, v82
	v_cvt_f16_f32_e32 v2, v83
	v_cvt_f16_f32_e32 v66, v85
	v_mfma_f32_16x16x32_f16 v[72:75], v[90:93], v[94:97], v[72:75]
	v_mov_b32_e32 v85, v3
	v_cndmask_b32_e64 v66, 0, v66, s[22:23]
	s_nop 0
	s_waitcnt lgkmcnt(0)
	v_mfma_f32_16x16x32_f16 v[76:79], v[90:93], v[128:131], v[62:65]
	v_mov_b32_e32 v92, v3
	s_nop 2
	v_cndmask_b32_e64 v0, 0, v72, s[10:11]
	v_cndmask_b32_e64 v37, 0, v73, s[14:15]
	v_cvt_f16_f32_e32 v63, v84
	v_mfma_f32_16x16x32_f16 v[94:97], v[98:101], v[94:97], v[68:71]
	v_cndmask_b32_e64 v64, 0, v74, s[16:17]
	v_cndmask_b32_e64 v65, 0, v75, s[20:21]
	v_cndmask_b32_e64 v63, 0, v63, s[18:19]
	v_cndmask_b32_e64 v68, 0, v1, s[12:13]
	v_cndmask_b32_e64 v69, v2, 0, s[10:11]
	v_add_f32_e32 v62, v217, v0
	v_cvt_pk_f16_f32 v1, v64, v65
	v_cvt_pk_f16_f32 v0, v0, v37
	v_mov_b32_e32 v2, v3
	v_pack_b32_f16 v67, v63, v66
	v_pack_b32_f16 v66, v68, v69
	v_mov_b32_e32 v68, v3
	v_mov_b32_e32 v69, v3
	v_add_f32_e32 v63, v219, v37
	v_add_f32_e32 v64, v220, v64
	v_mfma_f32_16x16x32_f16 v[70:73], v[0:3], v[66:69], 0
	v_add_f32_e32 v65, v221, v65
	v_cvt_pk_f16_f32 v83, v64, v65
	v_cvt_pk_f16_f32 v82, v62, v63
	v_mfma_f32_16x16x32_f16 v[66:69], v[66:69], v[0:3], 0
	v_mov_b32_e32 v84, v3
	s_nop 2
	v_cvt_pk_f16_f32 v0, v70, v71
	v_mov_b32_e32 v70, v3
	v_mov_b32_e32 v71, v3
	v_cvt_pk_f16_f32 v1, v72, v73
	v_cvt_pk_f16_f32 v69, v68, v69
	v_cvt_pk_f16_f32 v68, v66, v67
	v_mfma_f32_16x16x32_f16 v[62:65], v[0:3], v[82:85], v[62:65]
	v_mad_i64_i32 v[36:37], s[28:29], v36, s88, v[126:127]
	global_store_short v[36:37], v60, off
	v_mfma_f32_16x16x32_f16 v[72:75], v[68:71], v[0:3], 0
	v_cvt_f16_f32_e32 v82, v61
	v_subrev_u32_e32 v36, 61, v80
	v_xad_u32 v37, v102, -4, v168
	v_mfma_f32_16x16x32_f16 v[66:69], v[0:3], v[68:71], 0
	s_nop 0
	v_cvt_pk_f16_f32 v71, v64, v65
	s_nop 1
	v_cvt_pk_f16_f32 v1, v74, v75
	v_cvt_pk_f16_f32 v0, v72, v73
	ds_read2_b64 v[136:139], v229 offset1:4
	v_mfma_f32_16x16x32_f16 v[56:59], v[98:101], v[128:131], v[86:89]
	v_cvt_pk_f16_f32 v70, v62, v63
	v_mov_b32_e32 v72, v3
	v_mov_b32_e32 v73, v3
	v_cvt_pk_f16_f32 v85, v68, v69
	ds_read2_b64 v[128:131], v229 offset0:8 offset1:12
	v_cvt_pk_f16_f32 v84, v66, v67
	v_mov_b32_e32 v86, v3
	v_mov_b32_e32 v87, v3
	v_mfma_f32_16x16x32_f16 v[88:91], v[0:3], v[70:73], v[62:65]
	s_nop 0
	s_nop 0
	v_cndmask_b32_e64 v36, v37, v36, s[2:3]
	v_mfma_f32_16x16x32_f16 v[60:63], v[84:87], v[0:3], 0
	v_add_u32_e32 v83, v36, v175
	s_nop 2
	v_cvt_pk_f16_f32 v1, v90, v91
	v_cvt_pk_f16_f32 v0, v88, v89
	v_cvt_pk_f16_f32 v67, v54, v55
	v_cvt_pk_f16_f32 v66, v52, v53
	v_cvt_pk_f16_f32 v85, v62, v63
	v_cvt_pk_f16_f32 v84, v60, v61
	v_cvt_pk_f16_f32 v63, v50, v51
	v_cvt_pk_f16_f32 v62, v48, v49
	v_cvt_pk_f16_f32 v61, v42, v43
	v_cvt_pk_f16_f32 v60, v40, v41
	v_cvt_pk_f16_f32 v65, v46, v47
	v_cvt_pk_f16_f32 v64, v44, v45
	s_nop 0
	s_waitcnt lgkmcnt(1)
	v_mfma_f32_16x16x32_f16 v[68:71], v[136:139], v[60:63], 0
	v_add_u32_e32 v36, 0x1000, v229
	v_mov_b32_e32 v93, v3
	v_cvt_f16_f32_e32 v76, v76
	s_nop 0
	s_waitcnt lgkmcnt(0)
	v_mfma_f32_16x16x32_f16 v[98:101], v[128:131], v[64:67], v[68:71]
	ds_read2_b64 v[72:75], v36 offset0:64 offset1:68
	s_nop 1
	ds_read2_b64 v[68:71], v36 offset0:72 offset1:76
	v_cvt_f16_f32_e32 v36, v97
	v_cvt_f16_f32_e32 v97, v77
	v_mfma_f32_16x16x32_f16 v[84:87], v[84:87], v[0:3], v[88:91]
	v_cvt_f16_f32_e32 v0, v94
	v_cvt_f16_f32_e32 v1, v95
	v_cvt_f16_f32_e32 v2, v96
	v_cndmask_b32_e64 v96, v76, 0, s[12:13]
	v_cndmask_b32_e64 v0, 0, v0, s[10:11]
	v_cndmask_b32_e64 v37, 0, v1, s[14:15]
	v_cndmask_b32_e64 v1, 0, v2, s[16:17]
	v_cndmask_b32_e64 v2, 0, v36, s[20:21]
	v_pack_b32_f16 v1, v1, v2
	v_pack_b32_f16 v0, v0, v37
	v_mov_b32_e32 v2, v3
	v_mov_b32_e32 v36, v134
	v_mov_b32_e32 v37, v135
	v_mov_b32_e32 v38, v3
	v_mov_b32_e32 v39, v3
	v_mov_b32_e32 v94, v3
	v_mov_b32_e32 v95, v3
	v_mfma_f32_16x16x32_f16 v[88:91], v[0:3], v[36:39], v[98:101]
	v_cvt_pk_f16_f32 v1, v86, v87
	v_cvt_pk_f16_f32 v0, v84, v85
	v_cvt_f16_f32_e32 v56, v56
	v_cvt_f16_f32_e32 v98, v78
	v_cvt_f16_f32_e32 v99, v79
	s_nop 2
	v_cvt_pk_f16_f32 v91, v90, v91
	v_cvt_pk_f16_f32 v90, v88, v89
	v_cndmask_b32_e64 v97, 0, v97, s[10:11]
	v_cndmask_b32_e64 v98, v98, 0, s[18:19]
	v_mfma_f32_16x16x32_f16 v[84:87], v[0:3], v[90:93], 0
	v_add_u32_e32 v2, 0x800, v240
	ds_read2_b64 v[128:131], v2 offset0:64 offset1:144
	ds_read_b128 v[76:79], v182 offset:256
	v_mov_b32_e32 v90, v3
	v_mov_b32_e32 v91, v3
	v_cndmask_b32_e64 v99, v99, 0, s[22:23]
	ds_read_b64 v[88:89], v230 offset:5120
	ds_read_b128 v[132:135], v182 offset:320
	s_nop 3
	v_cvt_pk_f16_f32 v1, v86, v87
	v_cvt_pk_f16_f32 v0, v84, v85
	s_nop 0
	s_nop 0
	s_nop 0
	v_mov_b32_e32 v2, v3
	s_nop 0
	s_waitcnt lgkmcnt(3)
	v_mov_b32_e32 v92, v128
	v_mov_b32_e32 v93, v129
	ds_read_b64 v[84:85], v231 offset:5120
	s_nop 0
	s_waitcnt lgkmcnt(3)
	v_pk_mul_f32 v[42:43], v[42:43], v[78:79]
	v_pk_mul_f32 v[40:41], v[40:41], v[76:77]
	s_nop 0
	s_nop 0
	v_mfma_f32_16x16x32_f16 v[40:43], v[92:95], v[0:3], v[40:43]
	s_nop 0
	s_waitcnt lgkmcnt(1)
	v_pk_mul_f32 v[48:49], v[48:49], v[132:133]
	v_add_u32_e32 v76, 0xc00, v240
	ds_read2_b64 v[136:139], v76 offset0:96 offset1:176
	ds_read_b128 v[140:143], v182 offset:384
	v_mfma_f32_16x16x32_f16 v[40:43], v[88:91], v[36:39], v[40:43]
	v_mov_b32_e32 v88, v130
	v_mov_b32_e32 v89, v131
	v_pk_mul_f32 v[50:51], v[50:51], v[134:135]
	v_mov_b32_e32 v86, v3
	v_mov_b32_e32 v87, v3
	s_nop 0
	v_mfma_f32_16x16x32_f16 v[48:51], v[88:91], v[0:3], v[48:51]
	ds_read_b64 v[88:89], v232 offset:5120
	s_nop 0
	s_waitcnt lgkmcnt(2)
	v_mov_b32_e32 v92, v136
	v_mfma_f32_16x16x32_f16 v[48:51], v[84:87], v[36:39], v[48:51]
	s_nop 0
	s_nop 0
	v_mov_b32_e32 v93, v137
	v_pack_b32_f16 v76, v96, v97
	v_cndmask_b32_e64 v96, v56, 0, s[12:13]
	s_nop 0
	s_waitcnt lgkmcnt(1)
	v_pk_mul_f32 v[46:47], v[46:47], v[142:143]
	v_pk_mul_f32 v[44:45], v[44:45], v[140:141]
	ds_read_b128 v[84:87], v182 offset:448
	v_cvt_f16_f32_e32 v56, v57
	v_cvt_f16_f32_e32 v57, v58
	v_mfma_f32_16x16x32_f16 v[44:47], v[92:95], v[0:3], v[44:47]
	v_cvt_f16_f32_e32 v58, v59
	v_mov_b32_e32 v92, v138
	v_mov_b32_e32 v93, v139
	s_nop 0
	s_waitcnt lgkmcnt(1)
	v_mfma_f32_16x16x32_f16 v[44:47], v[88:91], v[36:39], v[44:47]
	ds_read_b64 v[88:89], v233 offset:5120
	s_nop 0
	s_nop 0
	v_cndmask_b32_e64 v78, v57, 0, s[18:19]
	v_cndmask_b32_e64 v79, v58, 0, s[22:23]
	v_pack_b32_f16 v77, v98, v99
	s_nop 0
	s_waitcnt lgkmcnt(1)
	v_pk_mul_f32 v[52:53], v[52:53], v[84:85]
	v_cndmask_b32_e64 v84, 0, v56, s[10:11]
	v_mfma_f32_16x16x32_f16 v[56:59], v[72:75], v[60:63], 0
	v_pack_b32_f16 v61, v78, v79
	v_mov_b32_e32 v78, v3
	v_mov_b32_e32 v79, v3
	v_mfma_f32_16x16x32_f16 v[56:59], v[68:71], v[64:67], v[56:59]
	v_mul_f32_e64 v54, v54, v86
	v_mul_f32_e64 v55, v55, v87
	v_pack_b32_f16 v60, v96, v84
	v_mov_b32_e32 v62, v3
	v_mov_b32_e32 v63, v3
	v_mfma_f32_16x16x32_f16 v[52:55], v[92:95], v[0:3], v[52:55]
	v_mfma_f32_16x16x32_f16 v[56:59], v[76:79], v[0:3], v[56:59]
	v_mad_i64_i32 v[0:1], s[28:29], v83, s88, v[126:127]
	global_store_short v[0:1], v82, off
	s_nop 0
	s_waitcnt lgkmcnt(0)
	v_mfma_f32_16x16x32_f16 v[52:55], v[88:91], v[36:39], v[52:55]
	v_subrev_u32_e32 v0, 48, v80
	v_add_u32_e32 v1, 0xef, v81
	v_cndmask_b32_e64 v0, v1, v0, s[2:3]
	v_mfma_f32_16x16x32_f16 v[36:39], v[60:63], v[36:39], v[56:59]
	v_add_u32_e32 v0, v0, v175
	v_mad_i64_i32 v[0:1], s[28:29], v0, s88, v[126:127]
	s_nop 5
	v_cvt_f16_f32_e32 v2, v36
	global_store_short v[0:1], v2, off
	v_subrev_u32_e32 v0, 47, v80
	v_add_u32_e32 v1, 0xee, v81
	v_cvt_f16_f32_e32 v2, v37
	v_cndmask_b32_e64 v0, v1, v0, s[2:3]
	v_add_u32_e32 v0, v0, v175
	v_mad_i64_i32 v[0:1], s[28:29], v0, s88, v[126:127]
	global_store_short v[0:1], v2, off
	v_subrev_u32_e32 v0, 46, v80
	v_add_u32_e32 v1, 0xed, v81
	v_cvt_f16_f32_e32 v2, v38
	v_cndmask_b32_e64 v0, v1, v0, s[2:3]
	v_add_u32_e32 v0, v0, v175
	v_mad_i64_i32 v[0:1], s[28:29], v0, s88, v[126:127]
	global_store_short v[0:1], v2, off
	v_subrev_u32_e32 v0, 45, v80
	v_add_u32_e32 v1, 0xec, v81
	v_cndmask_b32_e64 v0, v1, v0, s[2:3]
	v_cvt_f16_f32_e32 v2, v39
	v_add_u32_e32 v0, v0, v175
	v_mad_i64_i32 v[0:1], s[28:29], v0, s88, v[126:127]
	s_mov_b64 s[28:29], 0
	global_store_short v[0:1], v2, off

.LBB0_1035:
	s_or_b64 exec, exec, s[26:27]
	s_waitcnt lgkmcnt(0)
	s_barrier
	ds_read_b128 v[40:43], v212 offset:9216
	ds_read_b128 v[48:51], v212 offset:18496
	ds_read_b128 v[56:59], v212 offset:9280
	ds_read_b128 v[60:63], v212 offset:23040
	ds_read_b128 v[36:39], v212 offset:18432
	s_nop 0
	s_nop 0
	s_nop 0
	ds_read_b128 v[64:67], v212 offset:13824
	s_waitcnt lgkmcnt(1)
	v_mfma_f32_16x16x32_f16 v[52:55], v[40:43], v[36:39], 0
	s_nop 0
	s_nop 0
	s_nop 0
	ds_read_b128 v[68:71], v212 offset:13888
	ds_read_b128 v[72:75], v212 offset:23104
	v_add_u32_e32 v80, 0x1000, v217
	s_nop 0
	v_mfma_f32_16x16x32_f16 v[52:55], v[56:59], v[48:51], v[52:55]
	v_mov_b32_e32 v82, v3
	v_mov_b32_e32 v83, v3
	v_mov_b32_e32 v86, v3
	v_mfma_f32_16x16x32_f16 v[44:47], v[36:39], v[40:43], 0
	s_nop 3
	v_cvt_f16_f32_e32 v0, v52
	v_cvt_f16_f32_e32 v1, v54
	v_cvt_f16_f32_e32 v2, v55
	v_mfma_f32_16x16x32_f16 v[44:47], v[48:51], v[56:59], v[44:47]
	v_cndmask_b32_e64 v79, 0, v0, s[12:13]
	v_cvt_f16_f32_e32 v0, v53
	v_cndmask_b32_e64 v54, 0, v1, s[18:19]
	s_nop 0
	v_mfma_f32_16x16x32_f16 v[40:43], v[60:63], v[40:43], 0
	v_cndmask_b32_e64 v55, 0, v2, s[22:23]
	s_nop 1
	v_cndmask_b32_e64 v76, 0, v44, s[10:11]
	v_cndmask_b32_e64 v77, 0, v45, s[14:15]
	s_nop 0
	s_waitcnt lgkmcnt(2)
	v_mfma_f32_16x16x32_f16 v[36:39], v[36:39], v[64:67], 0
	v_cndmask_b32_e64 v52, 0, v46, s[16:17]
	v_cndmask_b32_e64 v78, 0, v47, s[20:21]
	v_cndmask_b32_e64 v53, v0, 0, s[10:11]
	v_mfma_f32_16x16x32_f16 v[44:47], v[60:63], v[64:67], 0
	v_cvt_pk_f16_f32 v1, v52, v78
	v_cvt_pk_f16_f32 v0, v76, v77
	v_mov_b32_e32 v2, v3
	s_nop 0
	s_waitcnt lgkmcnt(0)
	v_mfma_f32_16x16x32_f16 v[60:63], v[72:75], v[56:59], v[40:43]
	v_add_f32_e32 v56, v213, v76
	v_add_f32_e32 v57, v214, v77
	v_add_f32_e32 v58, v215, v52
	v_mfma_f32_16x16x32_f16 v[40:43], v[48:51], v[68:71], v[36:39]
	v_add_f32_e32 v59, v216, v78
	v_cvt_pk_f16_f32 v67, v18, v19
	v_cvt_pk_f16_f32 v66, v16, v17
	v_pack_b32_f16 v37, v54, v55
	v_pack_b32_f16 v36, v79, v53
	v_mov_b32_e32 v38, v3
	v_mov_b32_e32 v39, v3
	v_mfma_f32_16x16x32_f16 v[52:55], v[72:75], v[68:71], v[44:47]
	ds_read2_b64 v[68:71], v217 offset0:8 offset1:12
	v_cvt_pk_f16_f32 v65, v14, v15
	v_cvt_pk_f16_f32 v64, v12, v13
	v_mfma_f32_16x16x32_f16 v[48:51], v[0:3], v[36:39], 0
	v_cvt_pk_f16_f32 v45, v58, v59
	v_cvt_pk_f16_f32 v44, v56, v57
	v_mov_b32_e32 v46, v3
	v_mfma_f32_16x16x32_f16 v[36:39], v[36:39], v[0:3], 0
	v_mov_b32_e32 v47, v3
	s_nop 2
	v_cvt_pk_f16_f32 v1, v50, v51
	v_cvt_pk_f16_f32 v0, v48, v49
	v_mov_b32_e32 v50, v3
	v_mov_b32_e32 v51, v3
	v_cvt_pk_f16_f32 v49, v38, v39
	v_cvt_pk_f16_f32 v48, v36, v37
	v_mfma_f32_16x16x32_f16 v[44:47], v[0:3], v[44:47], v[56:59]
	v_mov_b32_e32 v87, v3
	v_mov_b32_e32 v90, v3
	v_mov_b32_e32 v91, v3
	v_mfma_f32_16x16x32_f16 v[36:39], v[48:51], v[0:3], 0
	ds_read2_b64 v[126:129], v217 offset1:4
	v_cvt_pk_f16_f32 v59, v10, v11
	v_cvt_pk_f16_f32 v58, v8, v9
	v_cvt_pk_f16_f32 v57, v6, v7
	v_mfma_f32_16x16x32_f16 v[48:51], v[0:3], v[48:51], 0
	v_cvt_pk_f16_f32 v56, v4, v5
	s_nop 2
	v_cvt_pk_f16_f32 v1, v38, v39
	v_cvt_pk_f16_f32 v0, v36, v37
	v_cvt_pk_f16_f32 v37, v46, v47
	v_cvt_pk_f16_f32 v36, v44, v45
	v_mov_b32_e32 v38, v3
	v_mov_b32_e32 v39, v3
	v_cvt_f16_f32_e32 v52, v52
	s_add_i32 s28, s76, 1
	v_mfma_f32_16x16x32_f16 v[44:47], v[0:3], v[36:39], v[44:47]
	v_cvt_pk_f16_f32 v37, v50, v51
	v_cvt_pk_f16_f32 v36, v48, v49
	v_mov_b32_e32 v50, v3
	v_mov_b32_e32 v51, v3
	v_mfma_f32_16x16x32_f16 v[36:39], v[36:39], v[0:3], 0
	s_nop 2
	v_cvt_pk_f16_f32 v1, v46, v47
	v_cvt_pk_f16_f32 v0, v44, v45
	s_nop 2
	v_cvt_pk_f16_f32 v49, v38, v39
	v_cvt_pk_f16_f32 v48, v36, v37
	s_nop 0
	s_nop 0
	s_waitcnt lgkmcnt(0)
	v_mfma_f32_16x16x32_f16 v[36:39], v[126:129], v[56:59], 0
	v_mfma_f32_16x16x32_f16 v[44:47], v[48:51], v[0:3], v[44:47]
	v_cvt_f16_f32_e32 v0, v60
	v_cvt_f16_f32_e32 v1, v61
	v_cvt_f16_f32_e32 v2, v62
	v_cvt_f16_f32_e32 v48, v63
	v_mfma_f32_16x16x32_f16 v[76:79], v[68:71], v[64:67], v[36:39]
	ds_read2_b64 v[72:75], v80 offset0:64 offset1:68
	ds_read2st64_b64 v[130:133], v218 offset0:20 offset1:25
	ds_read2_b64 v[68:71], v80 offset0:72 offset1:76
	s_nop 0
	s_nop 0
	v_cndmask_b32_e64 v0, 0, v0, s[10:11]
	v_cndmask_b32_e64 v49, 0, v1, s[14:15]
	v_cndmask_b32_e64 v1, 0, v2, s[16:17]
	v_cndmask_b32_e64 v2, 0, v48, s[20:21]
	v_pack_b32_f16 v1, v1, v2
	v_pack_b32_f16 v0, v0, v49
	v_mov_b32_e32 v2, v3
	s_nop 0
	s_waitcnt lgkmcnt(1)
	v_mov_b32_e32 v60, v130
	v_mov_b32_e32 v61, v131
	ds_read2_b64 v[126:129], v233 offset1:80
	v_mov_b32_e32 v62, v3
	v_mov_b32_e32 v63, v3
	v_cvt_f16_f32_e32 v36, v40
	ds_read_b128 v[134:137], v178
	v_cvt_f16_f32_e32 v40, v42
	v_mfma_f32_16x16x32_f16 v[48:51], v[0:3], v[60:63], v[76:79]
	v_cvt_pk_f16_f32 v1, v46, v47
	v_cvt_pk_f16_f32 v0, v44, v45
	v_cvt_f16_f32_e32 v37, v41
	v_mov_b32_e32 v78, v3
	v_mov_b32_e32 v79, v3
	s_nop 2
	v_cvt_pk_f16_f32 v77, v50, v51
	v_cvt_pk_f16_f32 v76, v48, v49
	v_cndmask_b32_e64 v88, v40, 0, s[18:19]
	v_mfma_f32_16x16x32_f16 v[56:59], v[72:75], v[56:59], 0
	v_cndmask_b32_e64 v36, v36, 0, s[12:13]
	v_cndmask_b32_e64 v37, 0, v37, s[10:11]
	v_mov_b32_e32 v74, v3
	v_mfma_f32_16x16x32_f16 v[44:47], v[0:3], v[76:79], 0
	ds_read_b64 v[76:77], v219 offset:5120
	ds_read_b128 v[138:141], v178 offset:64
	v_mov_b32_e32 v75, v3
	s_waitcnt lgkmcnt(4)
	v_mfma_f32_16x16x32_f16 v[56:59], v[68:71], v[64:67], v[56:59]
	s_nop 5
	v_cvt_pk_f16_f32 v1, v46, v47
	v_cvt_pk_f16_f32 v0, v44, v45
	s_nop 0
	s_nop 0
	s_nop 0
	s_nop 0
	s_waitcnt lgkmcnt(3)
	v_mov_b32_e32 v80, v126
	v_mov_b32_e32 v81, v127
	ds_read_b64 v[44:45], v220 offset:5120
	ds_read2_b64 v[142:145], v233 offset0:160 offset1:240
	s_nop 0
	s_waitcnt lgkmcnt(4)
	v_pk_mul_f32 v[50:51], v[6:7], v[136:137]
	v_pk_mul_f32 v[48:49], v[4:5], v[134:135]
	ds_read_b128 v[134:137], v178 offset:128
	s_nop 1
	v_mfma_f32_16x16x32_f16 v[48:51], v[80:83], v[0:3], v[48:51]
	v_cvt_f16_f32_e32 v80, v43
	v_cndmask_b32_e64 v89, v80, 0, s[22:23]
	s_nop 0
	s_waitcnt lgkmcnt(4)
	v_mfma_f32_16x16x32_f16 v[40:43], v[76:79], v[60:63], v[48:51]
	s_nop 3
	s_nop 0
	s_nop 0
	ds_read_b64 v[80:81], v221 offset:5120
	v_mov_b32_e32 v76, v128
	v_mov_b32_e32 v77, v129
	v_mov_b32_e32 v46, v3
	s_nop 0
	s_waitcnt lgkmcnt(4)
	v_pk_mul_f32 v[50:51], v[10:11], v[140:141]
	v_pk_mul_f32 v[48:49], v[8:9], v[138:139]
	v_mov_b32_e32 v47, v3
	ds_read_b128 v[126:129], v178 offset:192
	s_nop 0
	v_mfma_f32_16x16x32_f16 v[48:51], v[76:79], v[0:3], v[48:51]
	s_nop 0
	s_nop 0
	s_waitcnt lgkmcnt(3)
	v_mov_b32_e32 v84, v142
	v_mfma_f32_16x16x32_f16 v[48:51], v[44:47], v[60:63], v[48:51]
	s_nop 0
	s_nop 0
	v_mov_b32_e32 v85, v143
	v_pack_b32_f16 v77, v88, v89
	v_mov_b32_e32 v88, v144
	s_nop 0
	s_waitcnt lgkmcnt(2)
	v_pk_mul_f32 v[46:47], v[14:15], v[136:137]
	v_pk_mul_f32 v[44:45], v[12:13], v[134:135]
	v_mov_b32_e32 v89, v145
	v_pack_b32_f16 v76, v36, v37
	v_mfma_f32_16x16x32_f16 v[44:47], v[84:87], v[0:3], v[44:47]
	ds_read_b64 v[84:85], v222 offset:5120
	v_cndmask_b32_e64 v36, v52, 0, s[12:13]
	v_cvt_f16_f32_e32 v37, v53
	v_cndmask_b32_e64 v37, 0, v37, s[10:11]
	s_nop 0
	s_waitcnt lgkmcnt(2)
	v_mfma_f32_16x16x32_f16 v[44:47], v[80:83], v[60:63], v[44:47]
	s_nop 0
	s_nop 0
	v_pack_b32_f16 v72, v36, v37
	ds_read_b128 v[68:71], v223 offset:9216
	ds_read_b128 v[94:97], v223 offset:9280
	s_nop 0
	s_waitcnt lgkmcnt(3)
	v_pk_mul_f32 v[82:83], v[18:19], v[128:129]
	ds_read_b128 v[64:67], v223 offset:18432
	v_pk_mul_f32 v[80:81], v[16:17], v[126:127]
	s_nop 0
	ds_read_b128 v[98:101], v223 offset:23104
	v_mfma_f32_16x16x32_f16 v[78:81], v[88:91], v[0:3], v[80:83]
	ds_read_b128 v[90:93], v223 offset:18496
	s_nop 1
	v_cvt_f16_f32_e32 v82, v54
	v_cvt_f16_f32_e32 v83, v55
	s_nop 0
	s_waitcnt lgkmcnt(5)
	v_mfma_f32_16x16x32_f16 v[52:55], v[84:87], v[60:63], v[78:81]
	ds_read_b128 v[86:89], v223 offset:13824
	s_nop 1
	v_cndmask_b32_e64 v78, v82, 0, s[18:19]
	v_cndmask_b32_e64 v79, v83, 0, s[22:23]
	v_pack_b32_f16 v73, v78, v79
	v_mov_b32_e32 v78, v3
	v_mov_b32_e32 v79, v3
	v_add_u32_e32 v80, s69, v153
	v_add_u32_e32 v81, s68, v232
	v_mfma_f32_16x16x32_f16 v[56:59], v[76:79], v[0:3], v[56:59]
	ds_read_b128 v[76:79], v223 offset:23040
	v_subrev_u32_e32 v102, 64, v80
	v_add_u32_e32 v0, 0x7ff, v81
	v_mfma_f32_16x16x32_f16 v[58:61], v[72:75], v[60:63], v[56:59]
	v_cndmask_b32_e64 v0, v0, v102, s[2:3]
	v_add_u32_e32 v0, v0, v151
	v_mad_i64_i32 v[0:1], s[26:27], v0, s88, v[122:123]
	s_nop 0
	s_waitcnt lgkmcnt(4)
	v_mfma_f32_16x16x32_f16 v[82:85], v[68:71], v[64:67], 0
	s_nop 2
	v_cvt_f16_f32_e32 v2, v58
	v_cvt_f16_f32_e32 v60, v60
	ds_read_b128 v[126:129], v223 offset:13888
	global_store_short v[0:1], v2, off
	v_subrev_u32_e32 v0, 63, v80
	v_xad_u32 v1, v102, -2, v172
	v_cvt_f16_f32_e32 v2, v59
	s_nop 0
	v_mfma_f32_16x16x32_f16 v[72:75], v[64:67], v[68:71], 0
	v_cndmask_b32_e64 v0, v1, v0, s[2:3]
	v_add_u32_e32 v0, v0, v151
	v_mad_i64_i32 v[0:1], s[26:27], v0, s88, v[122:123]
	s_nop 0
	s_waitcnt lgkmcnt(2)
	v_mfma_f32_16x16x32_f16 v[62:65], v[64:67], v[86:89], 0
	global_store_short v[0:1], v2, off
	v_subrev_u32_e32 v0, 62, v80
	v_xad_u32 v1, v102, -3, v172
	v_mfma_f32_16x16x32_f16 v[82:85], v[94:97], v[90:93], v[82:85]
	v_cndmask_b32_e64 v36, v1, v0, s[2:3]
	v_add_u32_e32 v36, v36, v151
	s_nop 0
	s_waitcnt lgkmcnt(1)
	v_mfma_f32_16x16x32_f16 v[68:71], v[76:79], v[68:71], 0
	v_mfma_f32_16x16x32_f16 v[86:89], v[76:79], v[86:89], 0
	s_nop 2
	v_cvt_f16_f32_e32 v1, v82
	v_cvt_f16_f32_e32 v2, v83
	v_cvt_f16_f32_e32 v66, v85
	v_mfma_f32_16x16x32_f16 v[72:75], v[90:93], v[94:97], v[72:75]
	v_mov_b32_e32 v85, v3
	v_cndmask_b32_e64 v66, 0, v66, s[22:23]
	s_nop 0
	s_waitcnt lgkmcnt(0)
	v_mfma_f32_16x16x32_f16 v[76:79], v[90:93], v[126:129], v[62:65]
	v_mov_b32_e32 v92, v3
	s_nop 2
	v_cndmask_b32_e64 v0, 0, v72, s[10:11]
	v_cndmask_b32_e64 v37, 0, v73, s[14:15]
	v_cvt_f16_f32_e32 v63, v84
	v_mfma_f32_16x16x32_f16 v[94:97], v[98:101], v[94:97], v[68:71]
	v_cndmask_b32_e64 v64, 0, v74, s[16:17]
	v_cndmask_b32_e64 v65, 0, v75, s[20:21]
	v_cndmask_b32_e64 v63, 0, v63, s[18:19]
	v_cndmask_b32_e64 v68, 0, v1, s[12:13]
	v_cndmask_b32_e64 v69, v2, 0, s[10:11]
	v_add_f32_e32 v62, v213, v0
	v_cvt_pk_f16_f32 v1, v64, v65
	v_cvt_pk_f16_f32 v0, v0, v37
	v_mov_b32_e32 v2, v3
	v_pack_b32_f16 v67, v63, v66
	v_pack_b32_f16 v66, v68, v69
	v_mov_b32_e32 v68, v3
	v_mov_b32_e32 v69, v3
	v_add_f32_e32 v63, v214, v37
	v_add_f32_e32 v64, v215, v64
	v_mfma_f32_16x16x32_f16 v[70:73], v[0:3], v[66:69], 0
	v_add_f32_e32 v65, v216, v65
	v_cvt_pk_f16_f32 v83, v64, v65
	v_cvt_pk_f16_f32 v82, v62, v63
	v_mfma_f32_16x16x32_f16 v[66:69], v[66:69], v[0:3], 0
	v_mov_b32_e32 v84, v3
	s_nop 2
	v_cvt_pk_f16_f32 v0, v70, v71
	v_mov_b32_e32 v70, v3
	v_mov_b32_e32 v71, v3
	v_cvt_pk_f16_f32 v1, v72, v73
	v_cvt_pk_f16_f32 v69, v68, v69
	v_cvt_pk_f16_f32 v68, v66, v67
	v_mfma_f32_16x16x32_f16 v[62:65], v[0:3], v[82:85], v[62:65]
	v_mad_i64_i32 v[36:37], s[26:27], v36, s88, v[122:123]
	global_store_short v[36:37], v60, off
	v_mfma_f32_16x16x32_f16 v[72:75], v[68:71], v[0:3], 0
	v_cvt_f16_f32_e32 v82, v61
	v_subrev_u32_e32 v36, 61, v80
	v_xad_u32 v37, v102, -4, v172
	v_mfma_f32_16x16x32_f16 v[66:69], v[0:3], v[68:71], 0
	s_nop 0
	v_cvt_pk_f16_f32 v71, v64, v65
	s_nop 1
	v_cvt_pk_f16_f32 v1, v74, v75
	v_cvt_pk_f16_f32 v0, v72, v73
	ds_read2_b64 v[134:137], v224 offset1:4
	v_mfma_f32_16x16x32_f16 v[56:59], v[98:101], v[126:129], v[86:89]
	v_cvt_pk_f16_f32 v70, v62, v63
	v_mov_b32_e32 v72, v3
	v_mov_b32_e32 v73, v3
	v_cvt_pk_f16_f32 v85, v68, v69
	ds_read2_b64 v[126:129], v224 offset0:8 offset1:12
	v_cvt_pk_f16_f32 v84, v66, v67
	v_mov_b32_e32 v86, v3
	v_mov_b32_e32 v87, v3
	v_mfma_f32_16x16x32_f16 v[88:91], v[0:3], v[70:73], v[62:65]
	s_nop 0
	s_nop 0
	v_cndmask_b32_e64 v36, v37, v36, s[2:3]
	v_mfma_f32_16x16x32_f16 v[60:63], v[84:87], v[0:3], 0
	v_add_u32_e32 v83, v36, v151
	s_nop 2
	v_cvt_pk_f16_f32 v1, v90, v91
	v_cvt_pk_f16_f32 v0, v88, v89
	v_cvt_pk_f16_f32 v67, v54, v55
	v_cvt_pk_f16_f32 v66, v52, v53
	v_cvt_pk_f16_f32 v85, v62, v63
	v_cvt_pk_f16_f32 v84, v60, v61
	v_cvt_pk_f16_f32 v63, v50, v51
	v_cvt_pk_f16_f32 v62, v48, v49
	v_cvt_pk_f16_f32 v61, v42, v43
	v_cvt_pk_f16_f32 v60, v40, v41
	v_cvt_pk_f16_f32 v65, v46, v47
	v_cvt_pk_f16_f32 v64, v44, v45
	s_nop 0
	s_waitcnt lgkmcnt(1)
	v_mfma_f32_16x16x32_f16 v[68:71], v[134:137], v[60:63], 0
	v_add_u32_e32 v36, 0x1000, v224
	v_mov_b32_e32 v93, v3
	v_cvt_f16_f32_e32 v76, v76
	s_nop 0
	s_waitcnt lgkmcnt(0)
	v_mfma_f32_16x16x32_f16 v[98:101], v[126:129], v[64:67], v[68:71]
	ds_read2_b64 v[72:75], v36 offset0:64 offset1:68
	s_nop 1
	ds_read2_b64 v[68:71], v36 offset0:72 offset1:76
	v_cvt_f16_f32_e32 v36, v97
	v_cvt_f16_f32_e32 v97, v77
	v_mfma_f32_16x16x32_f16 v[84:87], v[84:87], v[0:3], v[88:91]
	v_cvt_f16_f32_e32 v0, v94
	v_cvt_f16_f32_e32 v1, v95
	v_cvt_f16_f32_e32 v2, v96
	v_cndmask_b32_e64 v96, v76, 0, s[12:13]
	v_cndmask_b32_e64 v0, 0, v0, s[10:11]
	v_cndmask_b32_e64 v37, 0, v1, s[14:15]
	v_cndmask_b32_e64 v1, 0, v2, s[16:17]
	v_cndmask_b32_e64 v2, 0, v36, s[20:21]
	v_pack_b32_f16 v1, v1, v2
	v_pack_b32_f16 v0, v0, v37
	v_mov_b32_e32 v2, v3
	v_mov_b32_e32 v36, v132
	v_mov_b32_e32 v37, v133
	v_mov_b32_e32 v38, v3
	v_mov_b32_e32 v39, v3
	v_mov_b32_e32 v94, v3
	v_mov_b32_e32 v95, v3
	v_mfma_f32_16x16x32_f16 v[88:91], v[0:3], v[36:39], v[98:101]
	v_cvt_pk_f16_f32 v1, v86, v87
	v_cvt_pk_f16_f32 v0, v84, v85
	v_cvt_f16_f32_e32 v56, v56
	v_cvt_f16_f32_e32 v98, v78
	v_cvt_f16_f32_e32 v99, v79
	s_nop 2
	v_cvt_pk_f16_f32 v91, v90, v91
	v_cvt_pk_f16_f32 v90, v88, v89
	v_cndmask_b32_e64 v97, 0, v97, s[10:11]
	v_cndmask_b32_e64 v98, v98, 0, s[18:19]
	v_mfma_f32_16x16x32_f16 v[84:87], v[0:3], v[90:93], 0
	v_add_u32_e32 v2, 0x800, v233
	ds_read2_b64 v[126:129], v2 offset0:64 offset1:144
	ds_read_b128 v[76:79], v178 offset:256
	v_mov_b32_e32 v90, v3
	v_mov_b32_e32 v91, v3
	v_cndmask_b32_e64 v99, v99, 0, s[22:23]
	ds_read_b64 v[88:89], v225 offset:5120
	ds_read_b128 v[130:133], v178 offset:320
	s_nop 3
	v_cvt_pk_f16_f32 v1, v86, v87
	v_cvt_pk_f16_f32 v0, v84, v85
	s_nop 0
	s_nop 0
	s_nop 0
	v_mov_b32_e32 v2, v3
	s_nop 0
	s_waitcnt lgkmcnt(3)
	v_mov_b32_e32 v92, v126
	v_mov_b32_e32 v93, v127
	ds_read_b64 v[84:85], v226 offset:5120
	s_nop 0
	s_waitcnt lgkmcnt(3)
	v_pk_mul_f32 v[42:43], v[42:43], v[78:79]
	v_pk_mul_f32 v[40:41], v[40:41], v[76:77]
	s_nop 0
	s_nop 0
	v_mfma_f32_16x16x32_f16 v[40:43], v[92:95], v[0:3], v[40:43]
	s_nop 0
	s_waitcnt lgkmcnt(1)
	v_pk_mul_f32 v[48:49], v[48:49], v[130:131]
	v_add_u32_e32 v76, 0xc00, v233
	ds_read2_b64 v[134:137], v76 offset0:96 offset1:176
	ds_read_b128 v[138:141], v178 offset:384
	v_mfma_f32_16x16x32_f16 v[40:43], v[88:91], v[36:39], v[40:43]
	v_mov_b32_e32 v88, v128
	v_mov_b32_e32 v89, v129
	v_pk_mul_f32 v[50:51], v[50:51], v[132:133]
	v_mov_b32_e32 v86, v3
	v_mov_b32_e32 v87, v3
	s_nop 0
	v_mfma_f32_16x16x32_f16 v[48:51], v[88:91], v[0:3], v[48:51]
	ds_read_b64 v[88:89], v227 offset:5120
	s_nop 0
	s_waitcnt lgkmcnt(2)
	v_mov_b32_e32 v92, v134
	v_mfma_f32_16x16x32_f16 v[48:51], v[84:87], v[36:39], v[48:51]
	s_nop 0
	s_nop 0
	v_mov_b32_e32 v93, v135
	v_pack_b32_f16 v76, v96, v97
	v_cndmask_b32_e64 v96, v56, 0, s[12:13]
	s_nop 0
	s_waitcnt lgkmcnt(1)
	v_pk_mul_f32 v[46:47], v[46:47], v[140:141]
	v_pk_mul_f32 v[44:45], v[44:45], v[138:139]
	ds_read_b128 v[84:87], v178 offset:448
	v_cvt_f16_f32_e32 v56, v57
	v_cvt_f16_f32_e32 v57, v58
	v_mfma_f32_16x16x32_f16 v[44:47], v[92:95], v[0:3], v[44:47]
	v_cvt_f16_f32_e32 v58, v59
	v_mov_b32_e32 v92, v136
	v_mov_b32_e32 v93, v137
	s_nop 0
	s_waitcnt lgkmcnt(1)
	v_mfma_f32_16x16x32_f16 v[44:47], v[88:91], v[36:39], v[44:47]
	ds_read_b64 v[88:89], v228 offset:5120
	s_nop 0
	s_nop 0
	v_cndmask_b32_e64 v78, v57, 0, s[18:19]
	v_cndmask_b32_e64 v79, v58, 0, s[22:23]
	v_pack_b32_f16 v77, v98, v99
	s_nop 0
	s_waitcnt lgkmcnt(1)
	v_pk_mul_f32 v[52:53], v[52:53], v[84:85]
	v_cndmask_b32_e64 v84, 0, v56, s[10:11]
	v_mfma_f32_16x16x32_f16 v[56:59], v[72:75], v[60:63], 0
	v_pack_b32_f16 v61, v78, v79
	v_mov_b32_e32 v78, v3
	v_mov_b32_e32 v79, v3
	v_mfma_f32_16x16x32_f16 v[56:59], v[68:71], v[64:67], v[56:59]
	v_mul_f32_e64 v54, v54, v86
	v_mul_f32_e64 v55, v55, v87
	v_pack_b32_f16 v60, v96, v84
	v_mov_b32_e32 v62, v3
	v_mov_b32_e32 v63, v3
	v_mfma_f32_16x16x32_f16 v[52:55], v[92:95], v[0:3], v[52:55]
	v_mfma_f32_16x16x32_f16 v[56:59], v[76:79], v[0:3], v[56:59]
	v_mad_i64_i32 v[0:1], s[26:27], v83, s88, v[122:123]
	global_store_short v[0:1], v82, off
	s_nop 0
	s_waitcnt lgkmcnt(0)
	v_mfma_f32_16x16x32_f16 v[52:55], v[88:91], v[36:39], v[52:55]
	v_subrev_u32_e32 v0, 48, v80
	v_add_u32_e32 v1, 0x7ef, v81
	v_cndmask_b32_e64 v0, v1, v0, s[2:3]
	v_mfma_f32_16x16x32_f16 v[36:39], v[60:63], v[36:39], v[56:59]
	v_add_u32_e32 v0, v0, v151
	v_mad_i64_i32 v[0:1], s[26:27], v0, s88, v[122:123]
	s_nop 5
	v_cvt_f16_f32_e32 v2, v36
	global_store_short v[0:1], v2, off
	v_subrev_u32_e32 v0, 47, v80
	v_add_u32_e32 v1, 0x7ee, v81
	v_cvt_f16_f32_e32 v2, v37
	v_cndmask_b32_e64 v0, v1, v0, s[2:3]
	v_add_u32_e32 v0, v0, v151
	v_mad_i64_i32 v[0:1], s[26:27], v0, s88, v[122:123]
	global_store_short v[0:1], v2, off
	v_subrev_u32_e32 v0, 46, v80
	v_add_u32_e32 v1, 0x7ed, v81
	v_cvt_f16_f32_e32 v2, v38
	v_cndmask_b32_e64 v0, v1, v0, s[2:3]
	v_add_u32_e32 v0, v0, v151
	v_mad_i64_i32 v[0:1], s[26:27], v0, s88, v[122:123]
	global_store_short v[0:1], v2, off
	v_subrev_u32_e32 v0, 45, v80
	v_add_u32_e32 v1, 0x7ec, v81
	v_cndmask_b32_e64 v0, v1, v0, s[2:3]
	v_cvt_f16_f32_e32 v2, v39
	v_add_u32_e32 v0, v0, v151
	v_mad_i64_i32 v[0:1], s[26:27], v0, s88, v[122:123]
	s_mov_b64 s[26:27], 0
	global_store_short v[0:1], v2, off
